# v3 plus: SwiGLU epilogue as eight independent silu chains (packed f32 for non-transcendental steps); phase-0 modulation GEMV issues its 32 weight-row loads up front with counted vmcnt
# baseline (speedup 1.0000x reference)
; #define PG8_STAGE(bufoff, gbase, voff) do { _Pragma("unroll") for (int _i = 0; _i < 2; ++_i) \
;         __builtin_amdgcn_global_load_lds((const unsigned*)((const char*)(gbase) + (voff)[_i]), (LAS unsigned*)(lds + (bufoff) + ldsw + _i * 8192), 16, 0, 0); } while (0)
; #define PG8_LDA(dst, b, h) do { _Pragma("unroll") for (int m = 0; m < 4; ++m) _Pragma("unroll") for (int k = 0; k < 2; ++k) dst[m][k] = *(const LAS bf16x8*)(lds + PG8_SA(b, h) + aoff + m * 2048 + k * 1024); } while (0)
; #define PG8_LDB(dst, b, h) do { _Pragma("unroll") for (int n = 0; n < 2; ++n) _Pragma("unroll") for (int k = 0; k < 2; ++k) dst[n][k] = *(const LAS bf16x8*)(lds + PG8_SB(b, h) + boff + n * 2048 + k * 1024); } while (0)
; #define PG8_WAIT_V(n) asm volatile("s_waitcnt vmcnt(" #n ")" ::: "memory")
; #define PG8_WAIT_L(n) asm volatile("s_waitcnt lgkmcnt(" #n ")" ::: "memory")
; #define PG8_BAR __builtin_amdgcn_s_barrier()
; #define PG8_SCHED __builtin_amdgcn_sched_barrier(0)
; template <class Epi>
; __device__ __forceinline__ void gemm_phase(LAS unsigned char* lds, const Gemm g, const StaticOrder& S, const Epi& E) {
;     ...
;         for (int t = 0; t < nt; t += 2) {
;             const bool last = (t == nt - 2);
;             const char* a1 = cA + (size_t)(t + 1) * kstep;
;             const char* a2 = last ? nA : cA + (size_t)(t + 2) * kstep; const char* b2 = last ? nB : cB + (size_t)(t + 2) * kstep;
;             const char* a3 = a2 + kstep; const char* b3 = b2 + kstep;
;             PG8_LDB(B0, 0, 0); PG8_SCHED; PG8_LDA(At, 0, 0); PG8_STAGE(PG8_SA(1, 1), a1 + hstep, voffA);
;             PG8_WAIT_L(8); PG8_BAR; PG8_WAIT_L(0); PG8_MMA(0, 0, At, B0); PG8_BAR; PG8_SCHED;
;             PG8_LDB(B1, 0, 1); PG8_STAGE(PG8_SB(0, 0), b2, voffB);
;             PG8_BAR; PG8_WAIT_L(0); PG8_MMA(0, 1, At, B1); PG8_BAR;
;             PG8_LDA(At, 0, 1); PG8_STAGE(PG8_SA(0, 0), a2, voffA);
;             PG8_BAR; PG8_WAIT_L(0); PG8_MMA(1, 0, At, B0); PG8_BAR; PG8_SCHED;
;             PG8_STAGE(PG8_SB(0, 1), b2 + hstep, voffB);
;             PG8_WAIT_V(6); PG8_BAR; PG8_MMA(1, 1, At, B1); PG8_BAR;
;             PG8_LDB(B0, 1, 0); PG8_SCHED; PG8_LDA(At, 1, 0); PG8_STAGE(PG8_SA(0, 1), a2 + hstep, voffA);
;             PG8_WAIT_L(8); PG8_BAR; PG8_WAIT_L(0); PG8_MMA(0, 0, At, B0); PG8_BAR; PG8_SCHED;
.LBB0_1250:
	s_add_u32 s22, s20, 0x100
	s_addc_u32 s23, s21, 0
	s_add_i32 s55, 0, 0x10000
	v_add_u32_e32 v142, s55, v144
	ds_read_b128 v[148:151], v142
	ds_read_b128 v[152:155], v142 offset:1024
	ds_read_b128 v[156:159], v142 offset:2048
	ds_read_b128 v[160:163], v142 offset:3072
	s_cmp_eq_u32 s45, 28
	s_cselect_b32 s43, s17, s23
	s_cselect_b32 s42, s16, s22
	s_cselect_b32 s25, s19, s44
	s_cselect_b32 s24, s18, s15
	v_lshl_add_u64 v[142:143], s[20:21], 0, v[138:139]
	s_add_i32 m0, s38, 0xc000
	ds_read_b128 v[164:167], v146
	ds_read_b128 v[168:171], v146 offset:1024
	ds_read_b128 v[172:175], v146 offset:2048
	ds_read_b128 v[186:189], v146 offset:3072
	ds_read_b128 v[210:213], v146 offset:4096
	ds_read_b128 v[214:217], v146 offset:5120
	ds_read_b128 v[218:221], v146 offset:6144
	ds_read_b128 v[222:225], v146 offset:7168
	global_load_lds_dwordx4 v[142:143], off
	v_lshl_add_u64 v[142:143], s[20:21], 0, v[140:141]
	s_add_i32 m0, s38, 0xe000
	s_nop 0
	global_load_lds_dwordx4 v[142:143], off
	s_waitcnt lgkmcnt(8)
	s_barrier
	s_waitcnt lgkmcnt(0)
	s_setprio 1
	s_waitcnt lgkmcnt(0)
	v_mfma_f32_16x16x32_bf16 v[126:129], v[148:151], v[164:167], v[126:129]
	v_mfma_f32_16x16x32_bf16 v[118:121], v[156:159], v[164:167], v[118:121]
	v_mfma_f32_16x16x32_bf16 v[110:113], v[148:151], v[172:175], v[110:113]
	v_mfma_f32_16x16x32_bf16 v[102:105], v[156:159], v[172:175], v[102:105]
	v_mfma_f32_16x16x32_bf16 v[92:95], v[148:151], v[210:213], v[92:95]
	v_mfma_f32_16x16x32_bf16 v[84:87], v[156:159], v[210:213], v[84:87]
	v_mfma_f32_16x16x32_bf16 v[76:79], v[148:151], v[218:221], v[76:79]
	v_mfma_f32_16x16x32_bf16 v[68:71], v[156:159], v[218:221], v[68:71]
	v_mfma_f32_16x16x32_bf16 v[126:129], v[152:155], v[168:171], v[126:129]
	v_mfma_f32_16x16x32_bf16 v[118:121], v[160:163], v[168:171], v[118:121]
	v_mfma_f32_16x16x32_bf16 v[110:113], v[152:155], v[186:189], v[110:113]
	v_mfma_f32_16x16x32_bf16 v[102:105], v[160:163], v[186:189], v[102:105]
	v_mfma_f32_16x16x32_bf16 v[92:95], v[152:155], v[214:217], v[92:95]
	v_mfma_f32_16x16x32_bf16 v[84:87], v[160:163], v[214:217], v[84:87]
	v_mfma_f32_16x16x32_bf16 v[76:79], v[152:155], v[222:225], v[76:79]
	v_mfma_f32_16x16x32_bf16 v[68:71], v[160:163], v[222:225], v[68:71]
	s_setprio 0
	s_barrier
	s_add_i32 s56, 0, 0x14000
	v_add_u32_e32 v142, s56, v144
	s_add_i32 s20, s55, s30
	ds_read_b128 v[226:229], v142
	ds_read_b128 v[230:233], v142 offset:1024
	ds_read_b128 v[234:237], v142 offset:2048
	ds_read_b128 v[238:241], v142 offset:3072
	v_lshl_add_u64 v[142:143], s[24:25], 0, v[134:135]
	s_mov_b32 m0, s20
	v_lshl_add_u64 v[176:177], s[24:25], 0, v[130:131]
	global_load_lds_dwordx4 v[142:143], off
	s_add_i32 m0, s20, 0x2000
	s_nop 0
	global_load_lds_dwordx4 v[176:177], off
	s_barrier
	s_waitcnt lgkmcnt(0)
	s_setprio 1
	s_waitcnt lgkmcnt(0)
	v_mfma_f32_16x16x32_bf16 v[122:125], v[226:229], v[164:167], v[122:125]
	v_mfma_f32_16x16x32_bf16 v[114:117], v[234:237], v[164:167], v[114:117]
	v_mfma_f32_16x16x32_bf16 v[106:109], v[226:229], v[172:175], v[106:109]
	v_mfma_f32_16x16x32_bf16 v[98:101], v[234:237], v[172:175], v[98:101]
	v_mfma_f32_16x16x32_bf16 v[88:91], v[226:229], v[210:213], v[88:91]
	v_mfma_f32_16x16x32_bf16 v[80:83], v[234:237], v[210:213], v[80:83]
	v_mfma_f32_16x16x32_bf16 v[72:75], v[226:229], v[218:221], v[72:75]
	v_mfma_f32_16x16x32_bf16 v[64:67], v[234:237], v[218:221], v[64:67]
	v_mfma_f32_16x16x32_bf16 v[122:125], v[230:233], v[168:171], v[122:125]
	v_mfma_f32_16x16x32_bf16 v[114:117], v[238:241], v[168:171], v[114:117]
	v_mfma_f32_16x16x32_bf16 v[106:109], v[230:233], v[186:189], v[106:109]
	v_mfma_f32_16x16x32_bf16 v[98:101], v[238:241], v[186:189], v[98:101]
	v_mfma_f32_16x16x32_bf16 v[88:91], v[230:233], v[214:217], v[88:91]
	v_mfma_f32_16x16x32_bf16 v[80:83], v[238:241], v[214:217], v[80:83]
	v_mfma_f32_16x16x32_bf16 v[72:75], v[230:233], v[222:225], v[72:75]
	v_mfma_f32_16x16x32_bf16 v[64:67], v[238:241], v[222:225], v[64:67]
	s_setprio 0
	s_mov_b32 m0, s38
	v_lshl_add_u64 v[198:199], s[42:43], 0, v[136:137]
	s_barrier
	ds_read_b128 v[164:167], v146 offset:16384
	ds_read_b128 v[168:171], v146 offset:17408
	ds_read_b128 v[172:175], v146 offset:18432
	ds_read_b128 v[186:189], v146 offset:19456
	ds_read_b128 v[210:213], v146 offset:20480
	ds_read_b128 v[214:217], v146 offset:21504
	ds_read_b128 v[218:221], v146 offset:22528
	ds_read_b128 v[222:225], v146 offset:23552
	global_load_lds_dwordx4 v[198:199], off
	v_lshl_add_u64 v[200:201], s[42:43], 0, v[132:133]
	s_mov_b32 m0, s39
	s_nop 0
	global_load_lds_dwordx4 v[200:201], off
	s_barrier
	s_waitcnt lgkmcnt(0)
	s_setprio 1
	s_waitcnt lgkmcnt(0)
	v_mfma_f32_16x16x32_bf16 v[60:63], v[148:151], v[164:167], v[60:63]
	v_mfma_f32_16x16x32_bf16 v[52:55], v[156:159], v[164:167], v[52:55]
	v_mfma_f32_16x16x32_bf16 v[44:47], v[148:151], v[172:175], v[44:47]
	v_mfma_f32_16x16x32_bf16 v[36:39], v[156:159], v[172:175], v[36:39]
	v_mfma_f32_16x16x32_bf16 v[28:31], v[148:151], v[210:213], v[28:31]
	v_mfma_f32_16x16x32_bf16 v[20:23], v[156:159], v[210:213], v[20:23]
	v_mfma_f32_16x16x32_bf16 v[12:15], v[148:151], v[218:221], v[12:15]
	v_mfma_f32_16x16x32_bf16 v[4:7], v[156:159], v[218:221], v[4:7]
	v_mfma_f32_16x16x32_bf16 v[60:63], v[152:155], v[168:171], v[60:63]
	v_mfma_f32_16x16x32_bf16 v[52:55], v[160:163], v[168:171], v[52:55]
	v_mfma_f32_16x16x32_bf16 v[44:47], v[152:155], v[186:189], v[44:47]
	v_mfma_f32_16x16x32_bf16 v[36:39], v[160:163], v[186:189], v[36:39]
	v_mfma_f32_16x16x32_bf16 v[28:31], v[152:155], v[214:217], v[28:31]
	v_mfma_f32_16x16x32_bf16 v[20:23], v[160:163], v[214:217], v[20:23]
	v_mfma_f32_16x16x32_bf16 v[12:15], v[152:155], v[222:225], v[12:15]
	v_mfma_f32_16x16x32_bf16 v[4:7], v[160:163], v[222:225], v[4:7]
	s_setprio 0
	s_barrier
; #define PG8_STAGE(bufoff, gbase, voff) do { _Pragma("unroll") for (int _i = 0; _i < 2; ++_i) \
;         __builtin_amdgcn_global_load_lds((const unsigned*)((const char*)(gbase) + (voff)[_i]), (LAS unsigned*)(lds + (bufoff) + ldsw + _i * 8192), 16, 0, 0); } while (0)
; #define PG8_LDA(dst, b, h) do { _Pragma("unroll") for (int m = 0; m < 4; ++m) _Pragma("unroll") for (int k = 0; k < 2; ++k) dst[m][k] = *(const LAS bf16x8*)(lds + PG8_SA(b, h) + aoff + m * 2048 + k * 1024); } while (0)
; #define PG8_LDB(dst, b, h) do { _Pragma("unroll") for (int n = 0; n < 2; ++n) _Pragma("unroll") for (int k = 0; k < 2; ++k) dst[n][k] = *(const LAS bf16x8*)(lds + PG8_SB(b, h) + boff + n * 2048 + k * 1024); } while (0)
; #define PG8_MMA(ai, bj, At, Bt) do { __builtin_amdgcn_s_setprio(1); _Pragma("unroll") for (int m = 0; m < 4; ++m) _Pragma("unroll") for (int n = 0; n < 2; ++n) _Pragma("unroll") for (int k = 0; k < 2; ++k) \
;         acc[ai][bj][m][n] = __builtin_amdgcn_mfma_f32_16x16x32_bf16(Bt[n][k], At[m][k], acc[ai][bj][m][n], 0, 0, 0); __builtin_amdgcn_s_setprio(0); } while (0)
; #define PG8_WAIT_V(n) asm volatile("s_waitcnt vmcnt(" #n ")" ::: "memory")
; #define PG8_WAIT_L(n) asm volatile("s_waitcnt lgkmcnt(" #n ")" ::: "memory")
; #define PG8_BAR __builtin_amdgcn_s_barrier()
; #define PG8_SCHED __builtin_amdgcn_sched_barrier(0)
; template <class Epi>
; __device__ __forceinline__ void gemm_phase(LAS unsigned char* lds, const Gemm g, const StaticOrder& S, const Epi& E) {
;     ...
;             PG8_WAIT_V(6); PG8_BAR; PG8_MMA(1, 1, At, B1); PG8_BAR;
;             PG8_LDB(B0, 1, 0); PG8_SCHED; PG8_LDA(At, 1, 0); PG8_STAGE(PG8_SA(0, 1), a2 + hstep, voffA);
;             PG8_WAIT_L(8); PG8_BAR; PG8_WAIT_L(0); PG8_MMA(0, 0, At, B0); PG8_BAR; PG8_SCHED;
;             PG8_LDB(B1, 1, 1); PG8_STAGE(PG8_SB(1, 0), b3, voffB);
;             PG8_BAR; PG8_WAIT_L(0); PG8_MMA(0, 1, At, B1); PG8_BAR;
;             PG8_LDA(At, 1, 1); PG8_STAGE(PG8_SA(1, 0), a3, voffA);
;             PG8_BAR; PG8_WAIT_L(0); PG8_MMA(1, 0, At, B0); PG8_BAR; PG8_SCHED;
	s_add_u32 s20, s24, 0x88000
	s_addc_u32 s21, s25, 0
	s_add_i32 s55, s56, s30
	v_lshl_add_u64 v[148:149], s[20:21], 0, v[134:135]
	s_mov_b32 m0, s55
	s_nop 0
	global_load_lds_dwordx4 v[148:149], off
	v_lshl_add_u64 v[148:149], s[20:21], 0, v[130:131]
	s_add_i32 m0, s55, 0x2000
	s_nop 0
	global_load_lds_dwordx4 v[148:149], off
	s_waitcnt vmcnt(6)
	s_barrier
	s_setprio 1
	v_mfma_f32_16x16x32_bf16 v[56:59], v[226:229], v[164:167], v[56:59]
	v_mfma_f32_16x16x32_bf16 v[48:51], v[234:237], v[164:167], v[48:51]
	v_mfma_f32_16x16x32_bf16 v[40:43], v[226:229], v[172:175], v[40:43]
	v_mfma_f32_16x16x32_bf16 v[32:35], v[234:237], v[172:175], v[32:35]
	v_mfma_f32_16x16x32_bf16 v[24:27], v[226:229], v[210:213], v[24:27]
	v_mfma_f32_16x16x32_bf16 v[16:19], v[234:237], v[210:213], v[16:19]
	v_mfma_f32_16x16x32_bf16 v[8:11], v[226:229], v[218:221], v[8:11]
	v_mfma_f32_16x16x32_bf16 v[0:3], v[234:237], v[218:221], v[0:3]
	v_mfma_f32_16x16x32_bf16 v[56:59], v[230:233], v[168:171], v[56:59]
	v_mfma_f32_16x16x32_bf16 v[48:51], v[238:241], v[168:171], v[48:51]
	v_mfma_f32_16x16x32_bf16 v[40:43], v[230:233], v[186:189], v[40:43]
	v_mfma_f32_16x16x32_bf16 v[32:35], v[238:241], v[186:189], v[32:35]
	v_mfma_f32_16x16x32_bf16 v[24:27], v[230:233], v[214:217], v[24:27]
	v_mfma_f32_16x16x32_bf16 v[16:19], v[238:241], v[214:217], v[16:19]
	v_mfma_f32_16x16x32_bf16 v[8:11], v[230:233], v[222:225], v[8:11]
	v_mfma_f32_16x16x32_bf16 v[0:3], v[238:241], v[222:225], v[0:3]
	s_setprio 0
	s_add_i32 s55, 0, 0x18000
	v_add_u32_e32 v147, s55, v144
	s_barrier
	ds_read_b128 v[148:151], v147
	ds_read_b128 v[152:155], v147 offset:1024
	ds_read_b128 v[156:159], v147 offset:2048
	ds_read_b128 v[160:163], v147 offset:3072
	s_add_u32 s20, s42, 0x88000
	s_addc_u32 s21, s43, 0
	s_mov_b32 m0, s46
	v_lshl_add_u64 v[226:227], s[20:21], 0, v[136:137]
	ds_read_b128 v[164:167], v146 offset:32768
	ds_read_b128 v[168:171], v146 offset:33792
	ds_read_b128 v[172:175], v146 offset:34816
	ds_read_b128 v[186:189], v146 offset:35840
	ds_read_b128 v[210:213], v146 offset:36864
	ds_read_b128 v[214:217], v146 offset:37888
	ds_read_b128 v[218:221], v146 offset:38912
	ds_read_b128 v[222:225], v146 offset:39936
	global_load_lds_dwordx4 v[226:227], off
	v_lshl_add_u64 v[226:227], s[20:21], 0, v[132:133]
	s_mov_b32 m0, s47
	s_nop 0
	global_load_lds_dwordx4 v[226:227], off
	s_waitcnt lgkmcnt(8)
	s_barrier
	s_waitcnt lgkmcnt(0)
	s_setprio 1
	s_waitcnt lgkmcnt(0)
	v_mfma_f32_16x16x32_bf16 v[126:129], v[148:151], v[164:167], v[126:129]
	v_mfma_f32_16x16x32_bf16 v[118:121], v[156:159], v[164:167], v[118:121]
	v_mfma_f32_16x16x32_bf16 v[110:113], v[148:151], v[172:175], v[110:113]
	v_mfma_f32_16x16x32_bf16 v[102:105], v[156:159], v[172:175], v[102:105]
	v_mfma_f32_16x16x32_bf16 v[92:95], v[148:151], v[210:213], v[92:95]
	v_mfma_f32_16x16x32_bf16 v[84:87], v[156:159], v[210:213], v[84:87]
	v_mfma_f32_16x16x32_bf16 v[76:79], v[148:151], v[218:221], v[76:79]
	v_mfma_f32_16x16x32_bf16 v[68:71], v[156:159], v[218:221], v[68:71]
	v_mfma_f32_16x16x32_bf16 v[126:129], v[152:155], v[168:171], v[126:129]
	v_mfma_f32_16x16x32_bf16 v[118:121], v[160:163], v[168:171], v[118:121]
	v_mfma_f32_16x16x32_bf16 v[110:113], v[152:155], v[186:189], v[110:113]
	v_mfma_f32_16x16x32_bf16 v[102:105], v[160:163], v[186:189], v[102:105]
	v_mfma_f32_16x16x32_bf16 v[92:95], v[152:155], v[214:217], v[92:95]
	v_mfma_f32_16x16x32_bf16 v[84:87], v[160:163], v[214:217], v[84:87]
	v_mfma_f32_16x16x32_bf16 v[76:79], v[152:155], v[222:225], v[76:79]
	v_mfma_f32_16x16x32_bf16 v[68:71], v[160:163], v[222:225], v[68:71]
	s_setprio 0
	s_barrier
	s_add_i32 s42, 0, 0x1c000
	s_add_i32 s20, s55, s30
	v_add_u32_e32 v147, s42, v144
	v_lshl_add_u64 v[142:143], v[142:143], 0, s[86:87]
	s_mov_b32 m0, s20
	ds_read_b128 v[226:229], v147
	ds_read_b128 v[230:233], v147 offset:1024
	ds_read_b128 v[234:237], v147 offset:2048
	ds_read_b128 v[238:241], v147 offset:3072
	global_load_lds_dwordx4 v[142:143], off
	v_lshl_add_u64 v[142:143], v[176:177], 0, s[86:87]
	s_add_i32 m0, s20, 0x2000
	s_nop 0
	global_load_lds_dwordx4 v[142:143], off
	s_barrier
	s_waitcnt lgkmcnt(0)
	s_setprio 1
	s_waitcnt lgkmcnt(0)
	v_mfma_f32_16x16x32_bf16 v[122:125], v[226:229], v[164:167], v[122:125]
	v_mfma_f32_16x16x32_bf16 v[114:117], v[234:237], v[164:167], v[114:117]
	v_mfma_f32_16x16x32_bf16 v[106:109], v[226:229], v[172:175], v[106:109]
	v_mfma_f32_16x16x32_bf16 v[98:101], v[234:237], v[172:175], v[98:101]
	v_mfma_f32_16x16x32_bf16 v[88:91], v[226:229], v[210:213], v[88:91]
	v_mfma_f32_16x16x32_bf16 v[80:83], v[234:237], v[210:213], v[80:83]
	v_mfma_f32_16x16x32_bf16 v[72:75], v[226:229], v[218:221], v[72:75]
	v_mfma_f32_16x16x32_bf16 v[64:67], v[234:237], v[218:221], v[64:67]
	v_mfma_f32_16x16x32_bf16 v[122:125], v[230:233], v[168:171], v[122:125]
	v_mfma_f32_16x16x32_bf16 v[114:117], v[238:241], v[168:171], v[114:117]
	v_mfma_f32_16x16x32_bf16 v[106:109], v[230:233], v[186:189], v[106:109]
	v_mfma_f32_16x16x32_bf16 v[98:101], v[238:241], v[186:189], v[98:101]
	v_mfma_f32_16x16x32_bf16 v[88:91], v[230:233], v[214:217], v[88:91]
	v_mfma_f32_16x16x32_bf16 v[80:83], v[238:241], v[214:217], v[80:83]
	v_mfma_f32_16x16x32_bf16 v[72:75], v[230:233], v[222:225], v[72:75]
	v_mfma_f32_16x16x32_bf16 v[64:67], v[238:241], v[222:225], v[64:67]
	s_setprio 0
	s_mov_b32 m0, s48
	v_lshl_add_u64 v[142:143], v[198:199], 0, s[86:87]
	s_barrier
	ds_read_b128 v[164:167], v146 offset:49152
	ds_read_b128 v[168:171], v146 offset:50176
	ds_read_b128 v[172:175], v146 offset:51200
	ds_read_b128 v[186:189], v146 offset:52224
	ds_read_b128 v[210:213], v146 offset:53248
	ds_read_b128 v[214:217], v146 offset:54272
	ds_read_b128 v[218:221], v146 offset:55296
	ds_read_b128 v[222:225], v146 offset:56320
	global_load_lds_dwordx4 v[142:143], off
	v_lshl_add_u64 v[142:143], v[200:201], 0, s[86:87]
	s_mov_b32 m0, s49
	s_nop 0
	global_load_lds_dwordx4 v[142:143], off
	s_barrier
; __device__ __forceinline__ unsigned cvt_pk_bf16(float lo, float hi) { unsigned r; asm volatile("v_cvt_pk_bf16_f32 %0, %1, %2" : "=v"(r) : "v"(lo), "v"(hi)); return r; }
; __device__ __forceinline__ float silu_f(float x) { return x * __builtin_amdgcn_rcpf(1.0f + __expf(-x)); }
; #define PG8_STAGE(bufoff, gbase, voff) do { _Pragma("unroll") for (int _i = 0; _i < 2; ++_i) \
;         __builtin_amdgcn_global_load_lds((const unsigned*)((const char*)(gbase) + (voff)[_i]), (LAS unsigned*)(lds + (bufoff) + ldsw + _i * 8192), 16, 0, 0); } while (0)
; #define PG8_MMA(ai, bj, At, Bt) do { __builtin_amdgcn_s_setprio(1); _Pragma("unroll") for (int m = 0; m < 4; ++m) _Pragma("unroll") for (int n = 0; n < 2; ++n) _Pragma("unroll") for (int k = 0; k < 2; ++k) \
;         acc[ai][bj][m][n] = __builtin_amdgcn_mfma_f32_16x16x32_bf16(Bt[n][k], At[m][k], acc[ai][bj][m][n], 0, 0, 0); __builtin_amdgcn_s_setprio(0); } while (0)
; #define PG8_WAIT_V(n) asm volatile("s_waitcnt vmcnt(" #n ")" ::: "memory")
; #define PG8_WAIT_L(n) asm volatile("s_waitcnt lgkmcnt(" #n ")" ::: "memory")
; #define PG8_BAR __builtin_amdgcn_s_barrier()
; template <class Epi>
; __device__ __forceinline__ void gemm_phase(LAS unsigned char* lds, const Gemm g, const StaticOrder& S, const Epi& E) {
;     ...
;             PG8_BAR; PG8_WAIT_L(0); PG8_MMA(1, 0, At, B0); PG8_BAR; PG8_SCHED;
;             PG8_STAGE(PG8_SB(1, 1), b3 + hstep, voffB);
;             PG8_WAIT_V(6); PG8_BAR; PG8_MMA(1, 1, At, B1); PG8_BAR;
;     __device__ __forceinline__ void operator()(const f32x4 (&acc)[2][2][4][2], const pg8::Unit& u, int wr, int wc, int fr, int fq) const {
;         const int row0 = u.pm * 256 + wr * 64 + fr, col0 = u.pn * 128 + wc * 32 + 8 * fq;
; #pragma unroll
;         for (int ai = 0; ai < 2; ++ai)
; #pragma unroll
;             for (int m = 0; m < 4; ++m) {
;                 bf16_t* rowp = H + (size_t)(row0 + ai * 128 + m * 16) * LDF + col0;
;                 const f32x4 a0 = acc[ai][0][m][0], a1 = acc[ai][0][m][1], b0 = acc[ai][1][m][0], b1 = acc[ai][1][m][1];
;                 float v[8];
; #pragma unroll
;                 for (int j = 0; j < 4; ++j) { v[j] = silu_f(a0[j]) * b0[j]; v[4 + j] = silu_f(a1[j]) * b1[j]; }
;                 u32x4 w; w.x = cvt_pk_bf16(v[0], v[1]); w.y = cvt_pk_bf16(v[2], v[3]); w.z = cvt_pk_bf16(v[4], v[5]); w.w = cvt_pk_bf16(v[6], v[7]);
;                 *(u32x4*)rowp = w;
	s_waitcnt lgkmcnt(0)
	s_setprio 1
	s_waitcnt lgkmcnt(0)
	v_mfma_f32_16x16x32_bf16 v[60:63], v[148:151], v[164:167], v[60:63]
	v_mfma_f32_16x16x32_bf16 v[52:55], v[156:159], v[164:167], v[52:55]
	v_mfma_f32_16x16x32_bf16 v[44:47], v[148:151], v[172:175], v[44:47]
	v_mfma_f32_16x16x32_bf16 v[36:39], v[156:159], v[172:175], v[36:39]
	v_mfma_f32_16x16x32_bf16 v[28:31], v[148:151], v[210:213], v[28:31]
	v_mfma_f32_16x16x32_bf16 v[20:23], v[156:159], v[210:213], v[20:23]
	v_mfma_f32_16x16x32_bf16 v[12:15], v[148:151], v[218:221], v[12:15]
	v_mfma_f32_16x16x32_bf16 v[4:7], v[156:159], v[218:221], v[4:7]
	v_mfma_f32_16x16x32_bf16 v[60:63], v[152:155], v[168:171], v[60:63]
	v_mfma_f32_16x16x32_bf16 v[52:55], v[160:163], v[168:171], v[52:55]
	v_mfma_f32_16x16x32_bf16 v[44:47], v[152:155], v[186:189], v[44:47]
	v_mfma_f32_16x16x32_bf16 v[36:39], v[160:163], v[186:189], v[36:39]
	v_mfma_f32_16x16x32_bf16 v[28:31], v[152:155], v[214:217], v[28:31]
	v_mfma_f32_16x16x32_bf16 v[20:23], v[160:163], v[214:217], v[20:23]
	v_mfma_f32_16x16x32_bf16 v[12:15], v[152:155], v[222:225], v[12:15]
	v_mfma_f32_16x16x32_bf16 v[4:7], v[160:163], v[222:225], v[4:7]
	s_setprio 0
	s_barrier
	s_add_u32 s20, s24, 0x88080
	s_addc_u32 s21, s25, 0
	s_add_i32 s24, s42, s30
	v_lshl_add_u64 v[142:143], s[20:21], 0, v[134:135]
	s_mov_b32 m0, s24
	s_nop 0
	global_load_lds_dwordx4 v[142:143], off
	v_lshl_add_u64 v[142:143], s[20:21], 0, v[130:131]
	s_add_i32 m0, s24, 0x2000
	s_nop 0
	global_load_lds_dwordx4 v[142:143], off
	s_waitcnt vmcnt(6)
	s_barrier
	s_setprio 1
	v_mfma_f32_16x16x32_bf16 v[56:59], v[226:229], v[164:167], v[56:59]
	v_mfma_f32_16x16x32_bf16 v[48:51], v[234:237], v[164:167], v[48:51]
	v_mfma_f32_16x16x32_bf16 v[40:43], v[226:229], v[172:175], v[40:43]
	v_mfma_f32_16x16x32_bf16 v[32:35], v[234:237], v[172:175], v[32:35]
	v_mfma_f32_16x16x32_bf16 v[24:27], v[226:229], v[210:213], v[24:27]
	v_mfma_f32_16x16x32_bf16 v[16:19], v[234:237], v[210:213], v[16:19]
	v_mfma_f32_16x16x32_bf16 v[8:11], v[226:229], v[218:221], v[8:11]
	v_mfma_f32_16x16x32_bf16 v[0:3], v[234:237], v[218:221], v[0:3]
	v_mfma_f32_16x16x32_bf16 v[56:59], v[230:233], v[168:171], v[56:59]
	v_mfma_f32_16x16x32_bf16 v[48:51], v[238:241], v[168:171], v[48:51]
	v_mfma_f32_16x16x32_bf16 v[40:43], v[230:233], v[186:189], v[40:43]
	v_mfma_f32_16x16x32_bf16 v[32:35], v[238:241], v[186:189], v[32:35]
	v_mfma_f32_16x16x32_bf16 v[24:27], v[230:233], v[214:217], v[24:27]
	v_mfma_f32_16x16x32_bf16 v[16:19], v[238:241], v[214:217], v[16:19]
	v_mfma_f32_16x16x32_bf16 v[8:11], v[230:233], v[222:225], v[8:11]
	v_mfma_f32_16x16x32_bf16 v[0:3], v[238:241], v[222:225], v[0:3]
	s_setprio 0
	s_add_i32 s45, s45, 2
	s_add_u32 s15, s15, 0x100
	s_addc_u32 s44, s44, 0
	s_cmp_gt_u32 s45, 29
	s_mov_b64 s[20:21], s[22:23]
	s_barrier
	s_cbranch_scc0 .LBB0_1250
	v_lshl_or_b32 v148, s54, 7, v145
	v_lshl_add_u32 v147, s53, 8, v97
	v_ashrrev_i32_e32 v149, 31, v148
	v_mov_b64_e32 v[142:143], s[26:27]
	s_movk_i32 s3, 0x2d00
	v_mad_i64_i32 v[150:151], s[20:21], v147, s3, v[142:143]
	s_and_b64 vcc, exec, s[40:41]
	s_mov_b32 s54, s52
	s_mov_b32 s53, s51
	s_mov_b64 s[22:23], s[18:19]
	v_lshlrev_b64 v[152:153], 1, v[148:149]
	v_mov_b32_e32 v176, 0xbfb8aa3b
	v_mov_b32_e32 v177, 0xbfb8aa3b
	v_lshl_add_u64 v[198:199], v[150:151], 0, v[152:153]
	s_mov_b64 s[20:21], 0x2d000
	v_pk_mul_f32 v[210:211], v[126:127], v[176:177]
	v_pk_mul_f32 v[212:213], v[128:129], v[176:177]
	v_pk_mul_f32 v[214:215], v[118:119], v[176:177]
	v_pk_mul_f32 v[216:217], v[120:121], v[176:177]
	v_exp_f32_e32 v210, v210
	v_exp_f32_e32 v211, v211
	v_exp_f32_e32 v212, v212
	v_exp_f32_e32 v213, v213
	v_exp_f32_e32 v214, v214
	v_exp_f32_e32 v215, v215
	v_exp_f32_e32 v216, v216
	v_exp_f32_e32 v217, v217
	v_pk_add_f32 v[210:211], v[210:211], 1.0 op_sel_hi:[1,0]
	v_pk_add_f32 v[212:213], v[212:213], 1.0 op_sel_hi:[1,0]
	v_pk_add_f32 v[214:215], v[214:215], 1.0 op_sel_hi:[1,0]
	v_pk_add_f32 v[216:217], v[216:217], 1.0 op_sel_hi:[1,0]
	v_rcp_f32_e32 v210, v210
	v_rcp_f32_e32 v211, v211
	v_rcp_f32_e32 v212, v212
	v_rcp_f32_e32 v213, v213
	v_rcp_f32_e32 v214, v214
	v_rcp_f32_e32 v215, v215
	v_rcp_f32_e32 v216, v216
	v_rcp_f32_e32 v217, v217
	v_pk_mul_f32 v[210:211], v[126:127], v[210:211]
	v_pk_mul_f32 v[212:213], v[128:129], v[212:213]
	v_pk_mul_f32 v[214:215], v[118:119], v[214:215]
	v_pk_mul_f32 v[216:217], v[120:121], v[216:217]
	v_pk_mul_f32 v[210:211], v[210:211], v[122:123]
	v_pk_mul_f32 v[212:213], v[212:213], v[124:125]
	v_pk_mul_f32 v[214:215], v[214:215], v[114:115]
	v_pk_mul_f32 v[216:217], v[216:217], v[116:117]
	v_cvt_pk_bf16_f32 v210, v210, v211
	v_cvt_pk_bf16_f32 v211, v212, v213
	v_cvt_pk_bf16_f32 v212, v214, v215
	v_cvt_pk_bf16_f32 v213, v216, v217
	global_store_dwordx4 v[198:199], v[210:213], off
	v_lshl_add_u64 v[198:199], v[198:199], 0, s[20:21]
	v_pk_mul_f32 v[218:219], v[110:111], v[176:177]
	v_pk_mul_f32 v[220:221], v[112:113], v[176:177]
	v_pk_mul_f32 v[222:223], v[102:103], v[176:177]
	v_pk_mul_f32 v[224:225], v[104:105], v[176:177]
	v_exp_f32_e32 v218, v218
	v_exp_f32_e32 v219, v219
	v_exp_f32_e32 v220, v220
	v_exp_f32_e32 v221, v221
	v_exp_f32_e32 v222, v222
	v_exp_f32_e32 v223, v223
	v_exp_f32_e32 v224, v224
	v_exp_f32_e32 v225, v225
	v_pk_add_f32 v[218:219], v[218:219], 1.0 op_sel_hi:[1,0]
	v_pk_add_f32 v[220:221], v[220:221], 1.0 op_sel_hi:[1,0]
	v_pk_add_f32 v[222:223], v[222:223], 1.0 op_sel_hi:[1,0]
	v_pk_add_f32 v[224:225], v[224:225], 1.0 op_sel_hi:[1,0]
	v_rcp_f32_e32 v218, v218
	v_rcp_f32_e32 v219, v219
	v_rcp_f32_e32 v220, v220
	v_rcp_f32_e32 v221, v221
	v_rcp_f32_e32 v222, v222
	v_rcp_f32_e32 v223, v223
	v_rcp_f32_e32 v224, v224
	v_rcp_f32_e32 v225, v225
; __device__ __forceinline__ unsigned cvt_pk_bf16(float lo, float hi) { unsigned r; asm volatile("v_cvt_pk_bf16_f32 %0, %1, %2" : "=v"(r) : "v"(lo), "v"(hi)); return r; }
; __device__ __forceinline__ float silu_f(float x) { return x * __builtin_amdgcn_rcpf(1.0f + __expf(-x)); }
;     __device__ __forceinline__ void operator()(const f32x4 (&acc)[2][2][4][2], const pg8::Unit& u, int wr, int wc, int fr, int fq) const {
;     ...
; #pragma unroll
;         for (int ai = 0; ai < 2; ++ai)
; #pragma unroll
;             for (int m = 0; m < 4; ++m) {
;                 bf16_t* rowp = H + (size_t)(row0 + ai * 128 + m * 16) * LDF + col0;
;                 const f32x4 a0 = acc[ai][0][m][0], a1 = acc[ai][0][m][1], b0 = acc[ai][1][m][0], b1 = acc[ai][1][m][1];
;                 float v[8];
; #pragma unroll
;                 for (int j = 0; j < 4; ++j) { v[j] = silu_f(a0[j]) * b0[j]; v[4 + j] = silu_f(a1[j]) * b1[j]; }
;                 u32x4 w; w.x = cvt_pk_bf16(v[0], v[1]); w.y = cvt_pk_bf16(v[2], v[3]); w.z = cvt_pk_bf16(v[4], v[5]); w.w = cvt_pk_bf16(v[6], v[7]);
;                 *(u32x4*)rowp = w;
	v_pk_mul_f32 v[218:219], v[110:111], v[218:219]
	v_pk_mul_f32 v[220:221], v[112:113], v[220:221]
	v_pk_mul_f32 v[222:223], v[102:103], v[222:223]
	v_pk_mul_f32 v[224:225], v[104:105], v[224:225]
	v_pk_mul_f32 v[218:219], v[218:219], v[106:107]
	v_pk_mul_f32 v[220:221], v[220:221], v[108:109]
	v_pk_mul_f32 v[222:223], v[222:223], v[98:99]
	v_pk_mul_f32 v[224:225], v[224:225], v[100:101]
	v_cvt_pk_bf16_f32 v218, v218, v219
	v_cvt_pk_bf16_f32 v219, v220, v221
	v_cvt_pk_bf16_f32 v220, v222, v223
	v_cvt_pk_bf16_f32 v221, v224, v225
	global_store_dwordx4 v[198:199], v[218:221], off
	v_lshl_add_u64 v[198:199], v[198:199], 0, s[20:21]
	v_pk_mul_f32 v[210:211], v[92:93], v[176:177]
	v_pk_mul_f32 v[212:213], v[94:95], v[176:177]
	v_pk_mul_f32 v[214:215], v[84:85], v[176:177]
	v_pk_mul_f32 v[216:217], v[86:87], v[176:177]
	v_exp_f32_e32 v210, v210
	v_exp_f32_e32 v211, v211
	v_exp_f32_e32 v212, v212
	v_exp_f32_e32 v213, v213
	v_exp_f32_e32 v214, v214
	v_exp_f32_e32 v215, v215
	v_exp_f32_e32 v216, v216
	v_exp_f32_e32 v217, v217
	v_pk_add_f32 v[210:211], v[210:211], 1.0 op_sel_hi:[1,0]
	v_pk_add_f32 v[212:213], v[212:213], 1.0 op_sel_hi:[1,0]
	v_pk_add_f32 v[214:215], v[214:215], 1.0 op_sel_hi:[1,0]
	v_pk_add_f32 v[216:217], v[216:217], 1.0 op_sel_hi:[1,0]
	v_rcp_f32_e32 v210, v210
	v_rcp_f32_e32 v211, v211
	v_rcp_f32_e32 v212, v212
	v_rcp_f32_e32 v213, v213
	v_rcp_f32_e32 v214, v214
	v_rcp_f32_e32 v215, v215
	v_rcp_f32_e32 v216, v216
	v_rcp_f32_e32 v217, v217
	v_pk_mul_f32 v[210:211], v[92:93], v[210:211]
	v_pk_mul_f32 v[212:213], v[94:95], v[212:213]
	v_pk_mul_f32 v[214:215], v[84:85], v[214:215]
	v_pk_mul_f32 v[216:217], v[86:87], v[216:217]
	v_pk_mul_f32 v[210:211], v[210:211], v[88:89]
	v_pk_mul_f32 v[212:213], v[212:213], v[90:91]
	v_pk_mul_f32 v[214:215], v[214:215], v[80:81]
	v_pk_mul_f32 v[216:217], v[216:217], v[82:83]
	v_cvt_pk_bf16_f32 v210, v210, v211
	v_cvt_pk_bf16_f32 v211, v212, v213
	v_cvt_pk_bf16_f32 v212, v214, v215
	v_cvt_pk_bf16_f32 v213, v216, v217
	global_store_dwordx4 v[198:199], v[210:213], off
	v_lshl_add_u64 v[198:199], v[198:199], 0, s[20:21]
	v_pk_mul_f32 v[218:219], v[76:77], v[176:177]
	v_pk_mul_f32 v[220:221], v[78:79], v[176:177]
	v_pk_mul_f32 v[222:223], v[68:69], v[176:177]
	v_pk_mul_f32 v[224:225], v[70:71], v[176:177]
	v_exp_f32_e32 v218, v218
	v_exp_f32_e32 v219, v219
	v_exp_f32_e32 v220, v220
	v_exp_f32_e32 v221, v221
	v_exp_f32_e32 v222, v222
	v_exp_f32_e32 v223, v223
	v_exp_f32_e32 v224, v224
	v_exp_f32_e32 v225, v225
	v_pk_add_f32 v[218:219], v[218:219], 1.0 op_sel_hi:[1,0]
	v_pk_add_f32 v[220:221], v[220:221], 1.0 op_sel_hi:[1,0]
	v_pk_add_f32 v[222:223], v[222:223], 1.0 op_sel_hi:[1,0]
	v_pk_add_f32 v[224:225], v[224:225], 1.0 op_sel_hi:[1,0]
	v_rcp_f32_e32 v218, v218
	v_rcp_f32_e32 v219, v219
	v_rcp_f32_e32 v220, v220
	v_rcp_f32_e32 v221, v221
	v_rcp_f32_e32 v222, v222
	v_rcp_f32_e32 v223, v223
	v_rcp_f32_e32 v224, v224
	v_rcp_f32_e32 v225, v225
	v_pk_mul_f32 v[218:219], v[76:77], v[218:219]
	v_pk_mul_f32 v[220:221], v[78:79], v[220:221]
	v_pk_mul_f32 v[222:223], v[68:69], v[222:223]
	v_pk_mul_f32 v[224:225], v[70:71], v[224:225]
	v_pk_mul_f32 v[218:219], v[218:219], v[72:73]
	v_pk_mul_f32 v[220:221], v[220:221], v[74:75]
	v_pk_mul_f32 v[222:223], v[222:223], v[64:65]
	v_pk_mul_f32 v[224:225], v[224:225], v[66:67]
	v_cvt_pk_bf16_f32 v218, v218, v219
	v_cvt_pk_bf16_f32 v219, v220, v221
	v_cvt_pk_bf16_f32 v220, v222, v223
	v_cvt_pk_bf16_f32 v221, v224, v225
	global_store_dwordx4 v[198:199], v[218:221], off
	s_mov_b64 s[20:21], 0xe1000
	v_lshl_add_u64 v[198:199], v[198:199], 0, s[20:21]
	s_mov_b64 s[20:21], 0x2d000
	v_pk_mul_f32 v[210:211], v[60:61], v[176:177]
	v_pk_mul_f32 v[212:213], v[62:63], v[176:177]
	v_pk_mul_f32 v[214:215], v[52:53], v[176:177]
	v_pk_mul_f32 v[216:217], v[54:55], v[176:177]
	v_exp_f32_e32 v210, v210
	v_exp_f32_e32 v211, v211
	v_exp_f32_e32 v212, v212
	v_exp_f32_e32 v213, v213
	v_exp_f32_e32 v214, v214
	v_exp_f32_e32 v215, v215
	v_exp_f32_e32 v216, v216
	v_exp_f32_e32 v217, v217
	v_pk_add_f32 v[210:211], v[210:211], 1.0 op_sel_hi:[1,0]
	v_pk_add_f32 v[212:213], v[212:213], 1.0 op_sel_hi:[1,0]
	v_pk_add_f32 v[214:215], v[214:215], 1.0 op_sel_hi:[1,0]
	v_pk_add_f32 v[216:217], v[216:217], 1.0 op_sel_hi:[1,0]
	v_rcp_f32_e32 v210, v210
	v_rcp_f32_e32 v211, v211
	v_rcp_f32_e32 v212, v212
	v_rcp_f32_e32 v213, v213
	v_rcp_f32_e32 v214, v214
	v_rcp_f32_e32 v215, v215
	v_rcp_f32_e32 v216, v216
	v_rcp_f32_e32 v217, v217
	v_pk_mul_f32 v[210:211], v[60:61], v[210:211]
	v_pk_mul_f32 v[212:213], v[62:63], v[212:213]
	v_pk_mul_f32 v[214:215], v[52:53], v[214:215]
	v_pk_mul_f32 v[216:217], v[54:55], v[216:217]
	v_pk_mul_f32 v[210:211], v[210:211], v[56:57]
	v_pk_mul_f32 v[212:213], v[212:213], v[58:59]
	v_pk_mul_f32 v[214:215], v[214:215], v[48:49]
; __device__ __forceinline__ unsigned cvt_pk_bf16(float lo, float hi) { unsigned r; asm volatile("v_cvt_pk_bf16_f32 %0, %1, %2" : "=v"(r) : "v"(lo), "v"(hi)); return r; }
; __device__ __forceinline__ float silu_f(float x) { return x * __builtin_amdgcn_rcpf(1.0f + __expf(-x)); }
;     __device__ __forceinline__ void operator()(const f32x4 (&acc)[2][2][4][2], const pg8::Unit& u, int wr, int wc, int fr, int fq) const {
;     ...
; #pragma unroll
;         for (int ai = 0; ai < 2; ++ai)
; #pragma unroll
;             for (int m = 0; m < 4; ++m) {
;                 bf16_t* rowp = H + (size_t)(row0 + ai * 128 + m * 16) * LDF + col0;
;                 const f32x4 a0 = acc[ai][0][m][0], a1 = acc[ai][0][m][1], b0 = acc[ai][1][m][0], b1 = acc[ai][1][m][1];
;                 float v[8];
; #pragma unroll
;                 for (int j = 0; j < 4; ++j) { v[j] = silu_f(a0[j]) * b0[j]; v[4 + j] = silu_f(a1[j]) * b1[j]; }
;                 u32x4 w; w.x = cvt_pk_bf16(v[0], v[1]); w.y = cvt_pk_bf16(v[2], v[3]); w.z = cvt_pk_bf16(v[4], v[5]); w.w = cvt_pk_bf16(v[6], v[7]);
;                 *(u32x4*)rowp = w;
	v_pk_mul_f32 v[216:217], v[216:217], v[50:51]
	v_cvt_pk_bf16_f32 v210, v210, v211
	v_cvt_pk_bf16_f32 v211, v212, v213
	v_cvt_pk_bf16_f32 v212, v214, v215
	v_cvt_pk_bf16_f32 v213, v216, v217
	global_store_dwordx4 v[198:199], v[210:213], off
	v_lshl_add_u64 v[198:199], v[198:199], 0, s[20:21]
	v_pk_mul_f32 v[218:219], v[44:45], v[176:177]
	v_pk_mul_f32 v[220:221], v[46:47], v[176:177]
	v_pk_mul_f32 v[222:223], v[36:37], v[176:177]
	v_pk_mul_f32 v[224:225], v[38:39], v[176:177]
	v_exp_f32_e32 v218, v218
	v_exp_f32_e32 v219, v219
	v_exp_f32_e32 v220, v220
	v_exp_f32_e32 v221, v221
	v_exp_f32_e32 v222, v222
	v_exp_f32_e32 v223, v223
	v_exp_f32_e32 v224, v224
	v_exp_f32_e32 v225, v225
	v_pk_add_f32 v[218:219], v[218:219], 1.0 op_sel_hi:[1,0]
	v_pk_add_f32 v[220:221], v[220:221], 1.0 op_sel_hi:[1,0]
	v_pk_add_f32 v[222:223], v[222:223], 1.0 op_sel_hi:[1,0]
	v_pk_add_f32 v[224:225], v[224:225], 1.0 op_sel_hi:[1,0]
	v_rcp_f32_e32 v218, v218
	v_rcp_f32_e32 v219, v219
	v_rcp_f32_e32 v220, v220
	v_rcp_f32_e32 v221, v221
	v_rcp_f32_e32 v222, v222
	v_rcp_f32_e32 v223, v223
	v_rcp_f32_e32 v224, v224
	v_rcp_f32_e32 v225, v225
	v_pk_mul_f32 v[218:219], v[44:45], v[218:219]
	v_pk_mul_f32 v[220:221], v[46:47], v[220:221]
	v_pk_mul_f32 v[222:223], v[36:37], v[222:223]
	v_pk_mul_f32 v[224:225], v[38:39], v[224:225]
	v_pk_mul_f32 v[218:219], v[218:219], v[40:41]
	v_pk_mul_f32 v[220:221], v[220:221], v[42:43]
	v_pk_mul_f32 v[222:223], v[222:223], v[32:33]
	v_pk_mul_f32 v[224:225], v[224:225], v[34:35]
	v_cvt_pk_bf16_f32 v218, v218, v219
	v_cvt_pk_bf16_f32 v219, v220, v221
	v_cvt_pk_bf16_f32 v220, v222, v223
	v_cvt_pk_bf16_f32 v221, v224, v225
	global_store_dwordx4 v[198:199], v[218:221], off
	v_lshl_add_u64 v[198:199], v[198:199], 0, s[20:21]
	v_pk_mul_f32 v[210:211], v[28:29], v[176:177]
	v_pk_mul_f32 v[212:213], v[30:31], v[176:177]
	v_pk_mul_f32 v[214:215], v[20:21], v[176:177]
	v_pk_mul_f32 v[216:217], v[22:23], v[176:177]
	v_exp_f32_e32 v210, v210
	v_exp_f32_e32 v211, v211
	v_exp_f32_e32 v212, v212
	v_exp_f32_e32 v213, v213
	v_exp_f32_e32 v214, v214
	v_exp_f32_e32 v215, v215
	v_exp_f32_e32 v216, v216
	v_exp_f32_e32 v217, v217
	v_pk_add_f32 v[210:211], v[210:211], 1.0 op_sel_hi:[1,0]
	v_pk_add_f32 v[212:213], v[212:213], 1.0 op_sel_hi:[1,0]
	v_pk_add_f32 v[214:215], v[214:215], 1.0 op_sel_hi:[1,0]
	v_pk_add_f32 v[216:217], v[216:217], 1.0 op_sel_hi:[1,0]
	v_rcp_f32_e32 v210, v210
	v_rcp_f32_e32 v211, v211
	v_rcp_f32_e32 v212, v212
	v_rcp_f32_e32 v213, v213
	v_rcp_f32_e32 v214, v214
	v_rcp_f32_e32 v215, v215
	v_rcp_f32_e32 v216, v216
	v_rcp_f32_e32 v217, v217
	v_pk_mul_f32 v[210:211], v[28:29], v[210:211]
	v_pk_mul_f32 v[212:213], v[30:31], v[212:213]
	v_pk_mul_f32 v[214:215], v[20:21], v[214:215]
	v_pk_mul_f32 v[216:217], v[22:23], v[216:217]
	v_pk_mul_f32 v[210:211], v[210:211], v[24:25]
	v_pk_mul_f32 v[212:213], v[212:213], v[26:27]
	v_pk_mul_f32 v[214:215], v[214:215], v[16:17]
	v_pk_mul_f32 v[216:217], v[216:217], v[18:19]
	v_cvt_pk_bf16_f32 v210, v210, v211
	v_cvt_pk_bf16_f32 v211, v212, v213
	v_cvt_pk_bf16_f32 v212, v214, v215
	v_cvt_pk_bf16_f32 v213, v216, v217
	global_store_dwordx4 v[198:199], v[210:213], off
	v_lshl_add_u64 v[198:199], v[198:199], 0, s[20:21]
	v_pk_mul_f32 v[218:219], v[12:13], v[176:177]
	v_pk_mul_f32 v[220:221], v[14:15], v[176:177]
	v_pk_mul_f32 v[222:223], v[4:5], v[176:177]
	v_pk_mul_f32 v[224:225], v[6:7], v[176:177]
	v_exp_f32_e32 v218, v218
	v_exp_f32_e32 v219, v219
	v_exp_f32_e32 v220, v220
	v_exp_f32_e32 v221, v221
	v_exp_f32_e32 v222, v222
	v_exp_f32_e32 v223, v223
	v_exp_f32_e32 v224, v224
	v_exp_f32_e32 v225, v225
	v_pk_add_f32 v[218:219], v[218:219], 1.0 op_sel_hi:[1,0]
	v_pk_add_f32 v[220:221], v[220:221], 1.0 op_sel_hi:[1,0]
	v_pk_add_f32 v[222:223], v[222:223], 1.0 op_sel_hi:[1,0]
	v_pk_add_f32 v[224:225], v[224:225], 1.0 op_sel_hi:[1,0]
	v_rcp_f32_e32 v218, v218
	v_rcp_f32_e32 v219, v219
	v_rcp_f32_e32 v220, v220
	v_rcp_f32_e32 v221, v221
	v_rcp_f32_e32 v222, v222
	v_rcp_f32_e32 v223, v223
	v_rcp_f32_e32 v224, v224
	v_rcp_f32_e32 v225, v225
	v_pk_mul_f32 v[218:219], v[12:13], v[218:219]
	v_pk_mul_f32 v[220:221], v[14:15], v[220:221]
	v_pk_mul_f32 v[222:223], v[4:5], v[222:223]
	v_pk_mul_f32 v[224:225], v[6:7], v[224:225]
	v_pk_mul_f32 v[218:219], v[218:219], v[8:9]
	v_pk_mul_f32 v[220:221], v[220:221], v[10:11]
	v_pk_mul_f32 v[222:223], v[222:223], v[0:1]
	v_pk_mul_f32 v[224:225], v[224:225], v[2:3]
	v_cvt_pk_bf16_f32 v218, v218, v219
	v_cvt_pk_bf16_f32 v219, v220, v221
	v_cvt_pk_bf16_f32 v220, v222, v223
	v_cvt_pk_bf16_f32 v221, v224, v225
	global_store_dwordx4 v[198:199], v[218:221], off
	s_mov_b64 s[20:21], s[16:17]
	s_cbranch_vccz .LBB0_1243
	s_waitcnt vmcnt(0)
	s_cmpk_gt_u32 s29, 0xff
	s_cbranch_scc1 .LBB0_1254
	s_barrier

; __device__ __forceinline__ void phase_prep(const Params& p, LAS unsigned char* lds, bool do_mod) {
;     ...
;         for (int kk = kr; kk < 512; kk += 16) {
;             const f32x4 w = *(const f32x4*)(p.w_mod + (size_t)(ks * 512 + kk) * MODW + cb * 128 + c4 * 4);
; #pragma unroll
;             for (int b = 0; b < 9; ++b) a[b] += w * sv[b * 512 + kk];
;         }
.LBB0_1387:
	global_load_dwordx4 v[84:87], v[40:41], off
	v_lshl_add_u64 v[40:41], v[40:41], 0, s[12:13]
	global_load_dwordx4 v[88:91], v[40:41], off
	v_lshl_add_u64 v[40:41], v[40:41], 0, s[12:13]
	global_load_dwordx4 v[92:95], v[40:41], off
	v_lshl_add_u64 v[40:41], v[40:41], 0, s[12:13]
	global_load_dwordx4 v[100:103], v[40:41], off
	v_lshl_add_u64 v[40:41], v[40:41], 0, s[12:13]
	global_load_dwordx4 v[104:107], v[40:41], off
	v_lshl_add_u64 v[40:41], v[40:41], 0, s[12:13]
	global_load_dwordx4 v[108:111], v[40:41], off
	v_lshl_add_u64 v[40:41], v[40:41], 0, s[12:13]
	global_load_dwordx4 v[112:115], v[40:41], off
	v_lshl_add_u64 v[40:41], v[40:41], 0, s[12:13]
	global_load_dwordx4 v[116:119], v[40:41], off
	v_lshl_add_u64 v[40:41], v[40:41], 0, s[12:13]
	global_load_dwordx4 v[120:123], v[40:41], off
	v_lshl_add_u64 v[40:41], v[40:41], 0, s[12:13]
	global_load_dwordx4 v[124:127], v[40:41], off
	v_lshl_add_u64 v[40:41], v[40:41], 0, s[12:13]
	global_load_dwordx4 v[128:131], v[40:41], off
	v_lshl_add_u64 v[40:41], v[40:41], 0, s[12:13]
	global_load_dwordx4 v[132:135], v[40:41], off
	v_lshl_add_u64 v[40:41], v[40:41], 0, s[12:13]
	global_load_dwordx4 v[136:139], v[40:41], off
	v_lshl_add_u64 v[40:41], v[40:41], 0, s[12:13]
	global_load_dwordx4 v[140:143], v[40:41], off
	v_lshl_add_u64 v[40:41], v[40:41], 0, s[12:13]
	global_load_dwordx4 v[144:147], v[40:41], off
	v_lshl_add_u64 v[40:41], v[40:41], 0, s[12:13]
	global_load_dwordx4 v[148:151], v[40:41], off
	v_lshl_add_u64 v[40:41], v[40:41], 0, s[12:13]
	global_load_dwordx4 v[152:155], v[40:41], off
	v_lshl_add_u64 v[40:41], v[40:41], 0, s[12:13]
	global_load_dwordx4 v[156:159], v[40:41], off
	v_lshl_add_u64 v[40:41], v[40:41], 0, s[12:13]
	global_load_dwordx4 v[160:163], v[40:41], off
	v_lshl_add_u64 v[40:41], v[40:41], 0, s[12:13]
	global_load_dwordx4 v[164:167], v[40:41], off
	v_lshl_add_u64 v[40:41], v[40:41], 0, s[12:13]
	global_load_dwordx4 v[168:171], v[40:41], off
	v_lshl_add_u64 v[40:41], v[40:41], 0, s[12:13]
	global_load_dwordx4 v[172:175], v[40:41], off
	v_lshl_add_u64 v[40:41], v[40:41], 0, s[12:13]
	global_load_dwordx4 v[212:215], v[40:41], off
	v_lshl_add_u64 v[40:41], v[40:41], 0, s[12:13]
	global_load_dwordx4 v[216:219], v[40:41], off
	v_lshl_add_u64 v[40:41], v[40:41], 0, s[12:13]
	global_load_dwordx4 v[220:223], v[40:41], off
	v_lshl_add_u64 v[40:41], v[40:41], 0, s[12:13]
	global_load_dwordx4 v[224:227], v[40:41], off
	v_lshl_add_u64 v[40:41], v[40:41], 0, s[12:13]
	global_load_dwordx4 v[228:231], v[40:41], off
	v_lshl_add_u64 v[40:41], v[40:41], 0, s[12:13]
	global_load_dwordx4 v[232:235], v[40:41], off
	v_lshl_add_u64 v[40:41], v[40:41], 0, s[12:13]
	global_load_dwordx4 v[236:239], v[40:41], off
	v_lshl_add_u64 v[40:41], v[40:41], 0, s[12:13]
	global_load_dwordx4 v[240:243], v[40:41], off
	v_lshl_add_u64 v[40:41], v[40:41], 0, s[12:13]
	global_load_dwordx4 v[186:189], v[40:41], off
	v_lshl_add_u64 v[40:41], v[40:41], 0, s[12:13]
	global_load_dwordx4 v[198:201], v[40:41], off
	ds_read2st64_b32 v[56:57], v49 offset1:8
	ds_read2st64_b32 v[58:59], v49 offset0:16 offset1:24
	ds_read2st64_b32 v[60:61], v49 offset0:32 offset1:40
	ds_read2st64_b32 v[62:63], v49 offset0:48 offset1:56
	ds_read_b32 v64, v49 offset:16384
	v_add_u32_e32 v49, 64, v49
	ds_read2st64_b32 v[244:245], v49 offset1:8
	ds_read2st64_b32 v[246:247], v49 offset0:16 offset1:24
	ds_read2st64_b32 v[248:249], v49 offset0:32 offset1:40
	ds_read2st64_b32 v[250:251], v49 offset0:48 offset1:56
	ds_read_b32 v74, v49 offset:16384
	v_add_u32_e32 v49, 64, v49
	s_waitcnt lgkmcnt(5)
	v_mov_b32_e32 v66, v57
	v_mov_b32_e32 v68, v59
	v_mov_b32_e32 v70, v61
	v_mov_b32_e32 v72, v63
	s_waitcnt vmcnt(31)
	v_pk_fma_f32 v[34:35], v[86:87], v[56:57], v[34:35] op_sel_hi:[1,0,1]
	v_pk_fma_f32 v[32:33], v[84:85], v[56:57], v[32:33] op_sel_hi:[1,0,1]
	v_pk_fma_f32 v[30:31], v[86:87], v[66:67], v[30:31] op_sel_hi:[1,0,1]
	v_pk_fma_f32 v[28:29], v[84:85], v[66:67], v[28:29] op_sel_hi:[1,0,1]
	v_pk_fma_f32 v[26:27], v[86:87], v[58:59], v[26:27] op_sel_hi:[1,0,1]
	v_pk_fma_f32 v[24:25], v[84:85], v[58:59], v[24:25] op_sel_hi:[1,0,1]
	v_pk_fma_f32 v[22:23], v[86:87], v[68:69], v[22:23] op_sel_hi:[1,0,1]
	v_pk_fma_f32 v[20:21], v[84:85], v[68:69], v[20:21] op_sel_hi:[1,0,1]
	v_pk_fma_f32 v[18:19], v[86:87], v[60:61], v[18:19] op_sel_hi:[1,0,1]
	v_pk_fma_f32 v[16:17], v[84:85], v[60:61], v[16:17] op_sel_hi:[1,0,1]
	v_pk_fma_f32 v[14:15], v[86:87], v[70:71], v[14:15] op_sel_hi:[1,0,1]
	v_pk_fma_f32 v[12:13], v[84:85], v[70:71], v[12:13] op_sel_hi:[1,0,1]
	v_pk_fma_f32 v[10:11], v[86:87], v[62:63], v[10:11] op_sel_hi:[1,0,1]
	v_pk_fma_f32 v[8:9], v[84:85], v[62:63], v[8:9] op_sel_hi:[1,0,1]
	v_pk_fma_f32 v[6:7], v[86:87], v[72:73], v[6:7] op_sel_hi:[1,0,1]
	v_pk_fma_f32 v[4:5], v[84:85], v[72:73], v[4:5] op_sel_hi:[1,0,1]
	v_pk_fma_f32 v[2:3], v[86:87], v[64:65], v[2:3] op_sel_hi:[1,0,1]
	v_pk_fma_f32 v[0:1], v[84:85], v[64:65], v[0:1] op_sel_hi:[1,0,1]
	ds_read2st64_b32 v[56:57], v49 offset1:8
	ds_read2st64_b32 v[58:59], v49 offset0:16 offset1:24
	ds_read2st64_b32 v[60:61], v49 offset0:32 offset1:40
	ds_read2st64_b32 v[62:63], v49 offset0:48 offset1:56
	ds_read_b32 v64, v49 offset:16384
	v_add_u32_e32 v49, 64, v49
	s_waitcnt lgkmcnt(5)
	v_mov_b32_e32 v76, v245
	v_mov_b32_e32 v78, v247
	v_mov_b32_e32 v80, v249
	v_mov_b32_e32 v82, v251
	s_waitcnt vmcnt(30)
; __device__ __forceinline__ void phase_prep(const Params& p, LAS unsigned char* lds, bool do_mod) {
;     ...
;         for (int kk = kr; kk < 512; kk += 16) {
;             const f32x4 w = *(const f32x4*)(p.w_mod + (size_t)(ks * 512 + kk) * MODW + cb * 128 + c4 * 4);
; #pragma unroll
;             for (int b = 0; b < 9; ++b) a[b] += w * sv[b * 512 + kk];
;         }
	v_pk_fma_f32 v[34:35], v[90:91], v[244:245], v[34:35] op_sel_hi:[1,0,1]
	v_pk_fma_f32 v[32:33], v[88:89], v[244:245], v[32:33] op_sel_hi:[1,0,1]
	v_pk_fma_f32 v[30:31], v[90:91], v[76:77], v[30:31] op_sel_hi:[1,0,1]
	v_pk_fma_f32 v[28:29], v[88:89], v[76:77], v[28:29] op_sel_hi:[1,0,1]
	v_pk_fma_f32 v[26:27], v[90:91], v[246:247], v[26:27] op_sel_hi:[1,0,1]
	v_pk_fma_f32 v[24:25], v[88:89], v[246:247], v[24:25] op_sel_hi:[1,0,1]
	v_pk_fma_f32 v[22:23], v[90:91], v[78:79], v[22:23] op_sel_hi:[1,0,1]
	v_pk_fma_f32 v[20:21], v[88:89], v[78:79], v[20:21] op_sel_hi:[1,0,1]
	v_pk_fma_f32 v[18:19], v[90:91], v[248:249], v[18:19] op_sel_hi:[1,0,1]
	v_pk_fma_f32 v[16:17], v[88:89], v[248:249], v[16:17] op_sel_hi:[1,0,1]
	v_pk_fma_f32 v[14:15], v[90:91], v[80:81], v[14:15] op_sel_hi:[1,0,1]
	v_pk_fma_f32 v[12:13], v[88:89], v[80:81], v[12:13] op_sel_hi:[1,0,1]
	v_pk_fma_f32 v[10:11], v[90:91], v[250:251], v[10:11] op_sel_hi:[1,0,1]
	v_pk_fma_f32 v[8:9], v[88:89], v[250:251], v[8:9] op_sel_hi:[1,0,1]
	v_pk_fma_f32 v[6:7], v[90:91], v[82:83], v[6:7] op_sel_hi:[1,0,1]
	v_pk_fma_f32 v[4:5], v[88:89], v[82:83], v[4:5] op_sel_hi:[1,0,1]
	v_pk_fma_f32 v[2:3], v[90:91], v[74:75], v[2:3] op_sel_hi:[1,0,1]
	v_pk_fma_f32 v[0:1], v[88:89], v[74:75], v[0:1] op_sel_hi:[1,0,1]
	ds_read2st64_b32 v[244:245], v49 offset1:8
	ds_read2st64_b32 v[246:247], v49 offset0:16 offset1:24
	ds_read2st64_b32 v[248:249], v49 offset0:32 offset1:40
	ds_read2st64_b32 v[250:251], v49 offset0:48 offset1:56
	ds_read_b32 v74, v49 offset:16384
	v_add_u32_e32 v49, 64, v49
	s_waitcnt lgkmcnt(5)
	v_mov_b32_e32 v66, v57
	v_mov_b32_e32 v68, v59
	v_mov_b32_e32 v70, v61
	v_mov_b32_e32 v72, v63
	s_waitcnt vmcnt(29)
	v_pk_fma_f32 v[34:35], v[94:95], v[56:57], v[34:35] op_sel_hi:[1,0,1]
	v_pk_fma_f32 v[32:33], v[92:93], v[56:57], v[32:33] op_sel_hi:[1,0,1]
	v_pk_fma_f32 v[30:31], v[94:95], v[66:67], v[30:31] op_sel_hi:[1,0,1]
	v_pk_fma_f32 v[28:29], v[92:93], v[66:67], v[28:29] op_sel_hi:[1,0,1]
	v_pk_fma_f32 v[26:27], v[94:95], v[58:59], v[26:27] op_sel_hi:[1,0,1]
	v_pk_fma_f32 v[24:25], v[92:93], v[58:59], v[24:25] op_sel_hi:[1,0,1]
	v_pk_fma_f32 v[22:23], v[94:95], v[68:69], v[22:23] op_sel_hi:[1,0,1]
	v_pk_fma_f32 v[20:21], v[92:93], v[68:69], v[20:21] op_sel_hi:[1,0,1]
	v_pk_fma_f32 v[18:19], v[94:95], v[60:61], v[18:19] op_sel_hi:[1,0,1]
	v_pk_fma_f32 v[16:17], v[92:93], v[60:61], v[16:17] op_sel_hi:[1,0,1]
	v_pk_fma_f32 v[14:15], v[94:95], v[70:71], v[14:15] op_sel_hi:[1,0,1]
	v_pk_fma_f32 v[12:13], v[92:93], v[70:71], v[12:13] op_sel_hi:[1,0,1]
	v_pk_fma_f32 v[10:11], v[94:95], v[62:63], v[10:11] op_sel_hi:[1,0,1]
	v_pk_fma_f32 v[8:9], v[92:93], v[62:63], v[8:9] op_sel_hi:[1,0,1]
	v_pk_fma_f32 v[6:7], v[94:95], v[72:73], v[6:7] op_sel_hi:[1,0,1]
	v_pk_fma_f32 v[4:5], v[92:93], v[72:73], v[4:5] op_sel_hi:[1,0,1]
	v_pk_fma_f32 v[2:3], v[94:95], v[64:65], v[2:3] op_sel_hi:[1,0,1]
	v_pk_fma_f32 v[0:1], v[92:93], v[64:65], v[0:1] op_sel_hi:[1,0,1]
	ds_read2st64_b32 v[56:57], v49 offset1:8
	ds_read2st64_b32 v[58:59], v49 offset0:16 offset1:24
	ds_read2st64_b32 v[60:61], v49 offset0:32 offset1:40
	ds_read2st64_b32 v[62:63], v49 offset0:48 offset1:56
	ds_read_b32 v64, v49 offset:16384
	v_add_u32_e32 v49, 64, v49
	s_waitcnt lgkmcnt(5)
	v_mov_b32_e32 v76, v245
	v_mov_b32_e32 v78, v247
	v_mov_b32_e32 v80, v249
	v_mov_b32_e32 v82, v251
	s_waitcnt vmcnt(28)
	v_pk_fma_f32 v[34:35], v[102:103], v[244:245], v[34:35] op_sel_hi:[1,0,1]
	v_pk_fma_f32 v[32:33], v[100:101], v[244:245], v[32:33] op_sel_hi:[1,0,1]
	v_pk_fma_f32 v[30:31], v[102:103], v[76:77], v[30:31] op_sel_hi:[1,0,1]
	v_pk_fma_f32 v[28:29], v[100:101], v[76:77], v[28:29] op_sel_hi:[1,0,1]
	v_pk_fma_f32 v[26:27], v[102:103], v[246:247], v[26:27] op_sel_hi:[1,0,1]
	v_pk_fma_f32 v[24:25], v[100:101], v[246:247], v[24:25] op_sel_hi:[1,0,1]
	v_pk_fma_f32 v[22:23], v[102:103], v[78:79], v[22:23] op_sel_hi:[1,0,1]
	v_pk_fma_f32 v[20:21], v[100:101], v[78:79], v[20:21] op_sel_hi:[1,0,1]
	v_pk_fma_f32 v[18:19], v[102:103], v[248:249], v[18:19] op_sel_hi:[1,0,1]
	v_pk_fma_f32 v[16:17], v[100:101], v[248:249], v[16:17] op_sel_hi:[1,0,1]
	v_pk_fma_f32 v[14:15], v[102:103], v[80:81], v[14:15] op_sel_hi:[1,0,1]
	v_pk_fma_f32 v[12:13], v[100:101], v[80:81], v[12:13] op_sel_hi:[1,0,1]
	v_pk_fma_f32 v[10:11], v[102:103], v[250:251], v[10:11] op_sel_hi:[1,0,1]
	v_pk_fma_f32 v[8:9], v[100:101], v[250:251], v[8:9] op_sel_hi:[1,0,1]
	v_pk_fma_f32 v[6:7], v[102:103], v[82:83], v[6:7] op_sel_hi:[1,0,1]
	v_pk_fma_f32 v[4:5], v[100:101], v[82:83], v[4:5] op_sel_hi:[1,0,1]
	v_pk_fma_f32 v[2:3], v[102:103], v[74:75], v[2:3] op_sel_hi:[1,0,1]
	v_pk_fma_f32 v[0:1], v[100:101], v[74:75], v[0:1] op_sel_hi:[1,0,1]
	ds_read2st64_b32 v[244:245], v49 offset1:8
	ds_read2st64_b32 v[246:247], v49 offset0:16 offset1:24
	ds_read2st64_b32 v[248:249], v49 offset0:32 offset1:40
	ds_read2st64_b32 v[250:251], v49 offset0:48 offset1:56
	ds_read_b32 v74, v49 offset:16384
	v_add_u32_e32 v49, 64, v49
	s_waitcnt lgkmcnt(5)
	v_mov_b32_e32 v66, v57
	v_mov_b32_e32 v68, v59
	v_mov_b32_e32 v70, v61
	v_mov_b32_e32 v72, v63
	s_waitcnt vmcnt(27)
; __device__ __forceinline__ void phase_prep(const Params& p, LAS unsigned char* lds, bool do_mod) {
;     ...
;         for (int kk = kr; kk < 512; kk += 16) {
;             const f32x4 w = *(const f32x4*)(p.w_mod + (size_t)(ks * 512 + kk) * MODW + cb * 128 + c4 * 4);
; #pragma unroll
;             for (int b = 0; b < 9; ++b) a[b] += w * sv[b * 512 + kk];
;         }
	v_pk_fma_f32 v[34:35], v[106:107], v[56:57], v[34:35] op_sel_hi:[1,0,1]
	v_pk_fma_f32 v[32:33], v[104:105], v[56:57], v[32:33] op_sel_hi:[1,0,1]
	v_pk_fma_f32 v[30:31], v[106:107], v[66:67], v[30:31] op_sel_hi:[1,0,1]
	v_pk_fma_f32 v[28:29], v[104:105], v[66:67], v[28:29] op_sel_hi:[1,0,1]
	v_pk_fma_f32 v[26:27], v[106:107], v[58:59], v[26:27] op_sel_hi:[1,0,1]
	v_pk_fma_f32 v[24:25], v[104:105], v[58:59], v[24:25] op_sel_hi:[1,0,1]
	v_pk_fma_f32 v[22:23], v[106:107], v[68:69], v[22:23] op_sel_hi:[1,0,1]
	v_pk_fma_f32 v[20:21], v[104:105], v[68:69], v[20:21] op_sel_hi:[1,0,1]
	v_pk_fma_f32 v[18:19], v[106:107], v[60:61], v[18:19] op_sel_hi:[1,0,1]
	v_pk_fma_f32 v[16:17], v[104:105], v[60:61], v[16:17] op_sel_hi:[1,0,1]
	v_pk_fma_f32 v[14:15], v[106:107], v[70:71], v[14:15] op_sel_hi:[1,0,1]
	v_pk_fma_f32 v[12:13], v[104:105], v[70:71], v[12:13] op_sel_hi:[1,0,1]
	v_pk_fma_f32 v[10:11], v[106:107], v[62:63], v[10:11] op_sel_hi:[1,0,1]
	v_pk_fma_f32 v[8:9], v[104:105], v[62:63], v[8:9] op_sel_hi:[1,0,1]
	v_pk_fma_f32 v[6:7], v[106:107], v[72:73], v[6:7] op_sel_hi:[1,0,1]
	v_pk_fma_f32 v[4:5], v[104:105], v[72:73], v[4:5] op_sel_hi:[1,0,1]
	v_pk_fma_f32 v[2:3], v[106:107], v[64:65], v[2:3] op_sel_hi:[1,0,1]
	v_pk_fma_f32 v[0:1], v[104:105], v[64:65], v[0:1] op_sel_hi:[1,0,1]
	ds_read2st64_b32 v[56:57], v49 offset1:8
	ds_read2st64_b32 v[58:59], v49 offset0:16 offset1:24
	ds_read2st64_b32 v[60:61], v49 offset0:32 offset1:40
	ds_read2st64_b32 v[62:63], v49 offset0:48 offset1:56
	ds_read_b32 v64, v49 offset:16384
	v_add_u32_e32 v49, 64, v49
	s_waitcnt lgkmcnt(5)
	v_mov_b32_e32 v76, v245
	v_mov_b32_e32 v78, v247
	v_mov_b32_e32 v80, v249
	v_mov_b32_e32 v82, v251
	s_waitcnt vmcnt(26)
	v_pk_fma_f32 v[34:35], v[110:111], v[244:245], v[34:35] op_sel_hi:[1,0,1]
	v_pk_fma_f32 v[32:33], v[108:109], v[244:245], v[32:33] op_sel_hi:[1,0,1]
	v_pk_fma_f32 v[30:31], v[110:111], v[76:77], v[30:31] op_sel_hi:[1,0,1]
	v_pk_fma_f32 v[28:29], v[108:109], v[76:77], v[28:29] op_sel_hi:[1,0,1]
	v_pk_fma_f32 v[26:27], v[110:111], v[246:247], v[26:27] op_sel_hi:[1,0,1]
	v_pk_fma_f32 v[24:25], v[108:109], v[246:247], v[24:25] op_sel_hi:[1,0,1]
	v_pk_fma_f32 v[22:23], v[110:111], v[78:79], v[22:23] op_sel_hi:[1,0,1]
	v_pk_fma_f32 v[20:21], v[108:109], v[78:79], v[20:21] op_sel_hi:[1,0,1]
	v_pk_fma_f32 v[18:19], v[110:111], v[248:249], v[18:19] op_sel_hi:[1,0,1]
	v_pk_fma_f32 v[16:17], v[108:109], v[248:249], v[16:17] op_sel_hi:[1,0,1]
	v_pk_fma_f32 v[14:15], v[110:111], v[80:81], v[14:15] op_sel_hi:[1,0,1]
	v_pk_fma_f32 v[12:13], v[108:109], v[80:81], v[12:13] op_sel_hi:[1,0,1]
	v_pk_fma_f32 v[10:11], v[110:111], v[250:251], v[10:11] op_sel_hi:[1,0,1]
	v_pk_fma_f32 v[8:9], v[108:109], v[250:251], v[8:9] op_sel_hi:[1,0,1]
	v_pk_fma_f32 v[6:7], v[110:111], v[82:83], v[6:7] op_sel_hi:[1,0,1]
	v_pk_fma_f32 v[4:5], v[108:109], v[82:83], v[4:5] op_sel_hi:[1,0,1]
	v_pk_fma_f32 v[2:3], v[110:111], v[74:75], v[2:3] op_sel_hi:[1,0,1]
	v_pk_fma_f32 v[0:1], v[108:109], v[74:75], v[0:1] op_sel_hi:[1,0,1]
	ds_read2st64_b32 v[244:245], v49 offset1:8
	ds_read2st64_b32 v[246:247], v49 offset0:16 offset1:24
	ds_read2st64_b32 v[248:249], v49 offset0:32 offset1:40
	ds_read2st64_b32 v[250:251], v49 offset0:48 offset1:56
	ds_read_b32 v74, v49 offset:16384
	v_add_u32_e32 v49, 64, v49
	s_waitcnt lgkmcnt(5)
	v_mov_b32_e32 v66, v57
	v_mov_b32_e32 v68, v59
	v_mov_b32_e32 v70, v61
	v_mov_b32_e32 v72, v63
	s_waitcnt vmcnt(25)
	v_pk_fma_f32 v[34:35], v[114:115], v[56:57], v[34:35] op_sel_hi:[1,0,1]
	v_pk_fma_f32 v[32:33], v[112:113], v[56:57], v[32:33] op_sel_hi:[1,0,1]
	v_pk_fma_f32 v[30:31], v[114:115], v[66:67], v[30:31] op_sel_hi:[1,0,1]
	v_pk_fma_f32 v[28:29], v[112:113], v[66:67], v[28:29] op_sel_hi:[1,0,1]
	v_pk_fma_f32 v[26:27], v[114:115], v[58:59], v[26:27] op_sel_hi:[1,0,1]
	v_pk_fma_f32 v[24:25], v[112:113], v[58:59], v[24:25] op_sel_hi:[1,0,1]
	v_pk_fma_f32 v[22:23], v[114:115], v[68:69], v[22:23] op_sel_hi:[1,0,1]
	v_pk_fma_f32 v[20:21], v[112:113], v[68:69], v[20:21] op_sel_hi:[1,0,1]
	v_pk_fma_f32 v[18:19], v[114:115], v[60:61], v[18:19] op_sel_hi:[1,0,1]
	v_pk_fma_f32 v[16:17], v[112:113], v[60:61], v[16:17] op_sel_hi:[1,0,1]
	v_pk_fma_f32 v[14:15], v[114:115], v[70:71], v[14:15] op_sel_hi:[1,0,1]
	v_pk_fma_f32 v[12:13], v[112:113], v[70:71], v[12:13] op_sel_hi:[1,0,1]
	v_pk_fma_f32 v[10:11], v[114:115], v[62:63], v[10:11] op_sel_hi:[1,0,1]
	v_pk_fma_f32 v[8:9], v[112:113], v[62:63], v[8:9] op_sel_hi:[1,0,1]
	v_pk_fma_f32 v[6:7], v[114:115], v[72:73], v[6:7] op_sel_hi:[1,0,1]
	v_pk_fma_f32 v[4:5], v[112:113], v[72:73], v[4:5] op_sel_hi:[1,0,1]
	v_pk_fma_f32 v[2:3], v[114:115], v[64:65], v[2:3] op_sel_hi:[1,0,1]
	v_pk_fma_f32 v[0:1], v[112:113], v[64:65], v[0:1] op_sel_hi:[1,0,1]
	ds_read2st64_b32 v[56:57], v49 offset1:8
	ds_read2st64_b32 v[58:59], v49 offset0:16 offset1:24
	ds_read2st64_b32 v[60:61], v49 offset0:32 offset1:40
	ds_read2st64_b32 v[62:63], v49 offset0:48 offset1:56
	ds_read_b32 v64, v49 offset:16384
	v_add_u32_e32 v49, 64, v49
	s_waitcnt lgkmcnt(5)
	v_mov_b32_e32 v76, v245
	v_mov_b32_e32 v78, v247
	v_mov_b32_e32 v80, v249
	v_mov_b32_e32 v82, v251
	s_waitcnt vmcnt(24)
; __device__ __forceinline__ void phase_prep(const Params& p, LAS unsigned char* lds, bool do_mod) {
;     ...
;         for (int kk = kr; kk < 512; kk += 16) {
;             const f32x4 w = *(const f32x4*)(p.w_mod + (size_t)(ks * 512 + kk) * MODW + cb * 128 + c4 * 4);
; #pragma unroll
;             for (int b = 0; b < 9; ++b) a[b] += w * sv[b * 512 + kk];
;         }
	v_pk_fma_f32 v[34:35], v[118:119], v[244:245], v[34:35] op_sel_hi:[1,0,1]
	v_pk_fma_f32 v[32:33], v[116:117], v[244:245], v[32:33] op_sel_hi:[1,0,1]
	v_pk_fma_f32 v[30:31], v[118:119], v[76:77], v[30:31] op_sel_hi:[1,0,1]
	v_pk_fma_f32 v[28:29], v[116:117], v[76:77], v[28:29] op_sel_hi:[1,0,1]
	v_pk_fma_f32 v[26:27], v[118:119], v[246:247], v[26:27] op_sel_hi:[1,0,1]
	v_pk_fma_f32 v[24:25], v[116:117], v[246:247], v[24:25] op_sel_hi:[1,0,1]
	v_pk_fma_f32 v[22:23], v[118:119], v[78:79], v[22:23] op_sel_hi:[1,0,1]
	v_pk_fma_f32 v[20:21], v[116:117], v[78:79], v[20:21] op_sel_hi:[1,0,1]
	v_pk_fma_f32 v[18:19], v[118:119], v[248:249], v[18:19] op_sel_hi:[1,0,1]
	v_pk_fma_f32 v[16:17], v[116:117], v[248:249], v[16:17] op_sel_hi:[1,0,1]
	v_pk_fma_f32 v[14:15], v[118:119], v[80:81], v[14:15] op_sel_hi:[1,0,1]
	v_pk_fma_f32 v[12:13], v[116:117], v[80:81], v[12:13] op_sel_hi:[1,0,1]
	v_pk_fma_f32 v[10:11], v[118:119], v[250:251], v[10:11] op_sel_hi:[1,0,1]
	v_pk_fma_f32 v[8:9], v[116:117], v[250:251], v[8:9] op_sel_hi:[1,0,1]
	v_pk_fma_f32 v[6:7], v[118:119], v[82:83], v[6:7] op_sel_hi:[1,0,1]
	v_pk_fma_f32 v[4:5], v[116:117], v[82:83], v[4:5] op_sel_hi:[1,0,1]
	v_pk_fma_f32 v[2:3], v[118:119], v[74:75], v[2:3] op_sel_hi:[1,0,1]
	v_pk_fma_f32 v[0:1], v[116:117], v[74:75], v[0:1] op_sel_hi:[1,0,1]
	ds_read2st64_b32 v[244:245], v49 offset1:8
	ds_read2st64_b32 v[246:247], v49 offset0:16 offset1:24
	ds_read2st64_b32 v[248:249], v49 offset0:32 offset1:40
	ds_read2st64_b32 v[250:251], v49 offset0:48 offset1:56
	ds_read_b32 v74, v49 offset:16384
	v_add_u32_e32 v49, 64, v49
	s_waitcnt lgkmcnt(5)
	v_mov_b32_e32 v66, v57
	v_mov_b32_e32 v68, v59
	v_mov_b32_e32 v70, v61
	v_mov_b32_e32 v72, v63
	s_waitcnt vmcnt(23)
	v_pk_fma_f32 v[34:35], v[122:123], v[56:57], v[34:35] op_sel_hi:[1,0,1]
	v_pk_fma_f32 v[32:33], v[120:121], v[56:57], v[32:33] op_sel_hi:[1,0,1]
	v_pk_fma_f32 v[30:31], v[122:123], v[66:67], v[30:31] op_sel_hi:[1,0,1]
	v_pk_fma_f32 v[28:29], v[120:121], v[66:67], v[28:29] op_sel_hi:[1,0,1]
	v_pk_fma_f32 v[26:27], v[122:123], v[58:59], v[26:27] op_sel_hi:[1,0,1]
	v_pk_fma_f32 v[24:25], v[120:121], v[58:59], v[24:25] op_sel_hi:[1,0,1]
	v_pk_fma_f32 v[22:23], v[122:123], v[68:69], v[22:23] op_sel_hi:[1,0,1]
	v_pk_fma_f32 v[20:21], v[120:121], v[68:69], v[20:21] op_sel_hi:[1,0,1]
	v_pk_fma_f32 v[18:19], v[122:123], v[60:61], v[18:19] op_sel_hi:[1,0,1]
	v_pk_fma_f32 v[16:17], v[120:121], v[60:61], v[16:17] op_sel_hi:[1,0,1]
	v_pk_fma_f32 v[14:15], v[122:123], v[70:71], v[14:15] op_sel_hi:[1,0,1]
	v_pk_fma_f32 v[12:13], v[120:121], v[70:71], v[12:13] op_sel_hi:[1,0,1]
	v_pk_fma_f32 v[10:11], v[122:123], v[62:63], v[10:11] op_sel_hi:[1,0,1]
	v_pk_fma_f32 v[8:9], v[120:121], v[62:63], v[8:9] op_sel_hi:[1,0,1]
	v_pk_fma_f32 v[6:7], v[122:123], v[72:73], v[6:7] op_sel_hi:[1,0,1]
	v_pk_fma_f32 v[4:5], v[120:121], v[72:73], v[4:5] op_sel_hi:[1,0,1]
	v_pk_fma_f32 v[2:3], v[122:123], v[64:65], v[2:3] op_sel_hi:[1,0,1]
	v_pk_fma_f32 v[0:1], v[120:121], v[64:65], v[0:1] op_sel_hi:[1,0,1]
	ds_read2st64_b32 v[56:57], v49 offset1:8
	ds_read2st64_b32 v[58:59], v49 offset0:16 offset1:24
	ds_read2st64_b32 v[60:61], v49 offset0:32 offset1:40
	ds_read2st64_b32 v[62:63], v49 offset0:48 offset1:56
	ds_read_b32 v64, v49 offset:16384
	v_add_u32_e32 v49, 64, v49
	s_waitcnt lgkmcnt(5)
	v_mov_b32_e32 v76, v245
	v_mov_b32_e32 v78, v247
	v_mov_b32_e32 v80, v249
	v_mov_b32_e32 v82, v251
	s_waitcnt vmcnt(22)
	v_pk_fma_f32 v[34:35], v[126:127], v[244:245], v[34:35] op_sel_hi:[1,0,1]
	v_pk_fma_f32 v[32:33], v[124:125], v[244:245], v[32:33] op_sel_hi:[1,0,1]
	v_pk_fma_f32 v[30:31], v[126:127], v[76:77], v[30:31] op_sel_hi:[1,0,1]
	v_pk_fma_f32 v[28:29], v[124:125], v[76:77], v[28:29] op_sel_hi:[1,0,1]
	v_pk_fma_f32 v[26:27], v[126:127], v[246:247], v[26:27] op_sel_hi:[1,0,1]
	v_pk_fma_f32 v[24:25], v[124:125], v[246:247], v[24:25] op_sel_hi:[1,0,1]
	v_pk_fma_f32 v[22:23], v[126:127], v[78:79], v[22:23] op_sel_hi:[1,0,1]
	v_pk_fma_f32 v[20:21], v[124:125], v[78:79], v[20:21] op_sel_hi:[1,0,1]
	v_pk_fma_f32 v[18:19], v[126:127], v[248:249], v[18:19] op_sel_hi:[1,0,1]
	v_pk_fma_f32 v[16:17], v[124:125], v[248:249], v[16:17] op_sel_hi:[1,0,1]
	v_pk_fma_f32 v[14:15], v[126:127], v[80:81], v[14:15] op_sel_hi:[1,0,1]
	v_pk_fma_f32 v[12:13], v[124:125], v[80:81], v[12:13] op_sel_hi:[1,0,1]
	v_pk_fma_f32 v[10:11], v[126:127], v[250:251], v[10:11] op_sel_hi:[1,0,1]
	v_pk_fma_f32 v[8:9], v[124:125], v[250:251], v[8:9] op_sel_hi:[1,0,1]
	v_pk_fma_f32 v[6:7], v[126:127], v[82:83], v[6:7] op_sel_hi:[1,0,1]
	v_pk_fma_f32 v[4:5], v[124:125], v[82:83], v[4:5] op_sel_hi:[1,0,1]
	v_pk_fma_f32 v[2:3], v[126:127], v[74:75], v[2:3] op_sel_hi:[1,0,1]
	v_pk_fma_f32 v[0:1], v[124:125], v[74:75], v[0:1] op_sel_hi:[1,0,1]
	ds_read2st64_b32 v[244:245], v49 offset1:8
	ds_read2st64_b32 v[246:247], v49 offset0:16 offset1:24
	ds_read2st64_b32 v[248:249], v49 offset0:32 offset1:40
	ds_read2st64_b32 v[250:251], v49 offset0:48 offset1:56
	ds_read_b32 v74, v49 offset:16384
	v_add_u32_e32 v49, 64, v49
	s_waitcnt lgkmcnt(5)
	v_mov_b32_e32 v66, v57
	v_mov_b32_e32 v68, v59
	v_mov_b32_e32 v70, v61
	v_mov_b32_e32 v72, v63
	s_waitcnt vmcnt(21)
; __device__ __forceinline__ void phase_prep(const Params& p, LAS unsigned char* lds, bool do_mod) {
;     ...
;         for (int kk = kr; kk < 512; kk += 16) {
;             const f32x4 w = *(const f32x4*)(p.w_mod + (size_t)(ks * 512 + kk) * MODW + cb * 128 + c4 * 4);
; #pragma unroll
;             for (int b = 0; b < 9; ++b) a[b] += w * sv[b * 512 + kk];
;         }
	v_pk_fma_f32 v[34:35], v[130:131], v[56:57], v[34:35] op_sel_hi:[1,0,1]
	v_pk_fma_f32 v[32:33], v[128:129], v[56:57], v[32:33] op_sel_hi:[1,0,1]
	v_pk_fma_f32 v[30:31], v[130:131], v[66:67], v[30:31] op_sel_hi:[1,0,1]
	v_pk_fma_f32 v[28:29], v[128:129], v[66:67], v[28:29] op_sel_hi:[1,0,1]
	v_pk_fma_f32 v[26:27], v[130:131], v[58:59], v[26:27] op_sel_hi:[1,0,1]
	v_pk_fma_f32 v[24:25], v[128:129], v[58:59], v[24:25] op_sel_hi:[1,0,1]
	v_pk_fma_f32 v[22:23], v[130:131], v[68:69], v[22:23] op_sel_hi:[1,0,1]
	v_pk_fma_f32 v[20:21], v[128:129], v[68:69], v[20:21] op_sel_hi:[1,0,1]
	v_pk_fma_f32 v[18:19], v[130:131], v[60:61], v[18:19] op_sel_hi:[1,0,1]
	v_pk_fma_f32 v[16:17], v[128:129], v[60:61], v[16:17] op_sel_hi:[1,0,1]
	v_pk_fma_f32 v[14:15], v[130:131], v[70:71], v[14:15] op_sel_hi:[1,0,1]
	v_pk_fma_f32 v[12:13], v[128:129], v[70:71], v[12:13] op_sel_hi:[1,0,1]
	v_pk_fma_f32 v[10:11], v[130:131], v[62:63], v[10:11] op_sel_hi:[1,0,1]
	v_pk_fma_f32 v[8:9], v[128:129], v[62:63], v[8:9] op_sel_hi:[1,0,1]
	v_pk_fma_f32 v[6:7], v[130:131], v[72:73], v[6:7] op_sel_hi:[1,0,1]
	v_pk_fma_f32 v[4:5], v[128:129], v[72:73], v[4:5] op_sel_hi:[1,0,1]
	v_pk_fma_f32 v[2:3], v[130:131], v[64:65], v[2:3] op_sel_hi:[1,0,1]
	v_pk_fma_f32 v[0:1], v[128:129], v[64:65], v[0:1] op_sel_hi:[1,0,1]
	ds_read2st64_b32 v[56:57], v49 offset1:8
	ds_read2st64_b32 v[58:59], v49 offset0:16 offset1:24
	ds_read2st64_b32 v[60:61], v49 offset0:32 offset1:40
	ds_read2st64_b32 v[62:63], v49 offset0:48 offset1:56
	ds_read_b32 v64, v49 offset:16384
	v_add_u32_e32 v49, 64, v49
	s_waitcnt lgkmcnt(5)
	v_mov_b32_e32 v76, v245
	v_mov_b32_e32 v78, v247
	v_mov_b32_e32 v80, v249
	v_mov_b32_e32 v82, v251
	s_waitcnt vmcnt(20)
	v_pk_fma_f32 v[34:35], v[134:135], v[244:245], v[34:35] op_sel_hi:[1,0,1]
	v_pk_fma_f32 v[32:33], v[132:133], v[244:245], v[32:33] op_sel_hi:[1,0,1]
	v_pk_fma_f32 v[30:31], v[134:135], v[76:77], v[30:31] op_sel_hi:[1,0,1]
	v_pk_fma_f32 v[28:29], v[132:133], v[76:77], v[28:29] op_sel_hi:[1,0,1]
	v_pk_fma_f32 v[26:27], v[134:135], v[246:247], v[26:27] op_sel_hi:[1,0,1]
	v_pk_fma_f32 v[24:25], v[132:133], v[246:247], v[24:25] op_sel_hi:[1,0,1]
	v_pk_fma_f32 v[22:23], v[134:135], v[78:79], v[22:23] op_sel_hi:[1,0,1]
	v_pk_fma_f32 v[20:21], v[132:133], v[78:79], v[20:21] op_sel_hi:[1,0,1]
	v_pk_fma_f32 v[18:19], v[134:135], v[248:249], v[18:19] op_sel_hi:[1,0,1]
	v_pk_fma_f32 v[16:17], v[132:133], v[248:249], v[16:17] op_sel_hi:[1,0,1]
	v_pk_fma_f32 v[14:15], v[134:135], v[80:81], v[14:15] op_sel_hi:[1,0,1]
	v_pk_fma_f32 v[12:13], v[132:133], v[80:81], v[12:13] op_sel_hi:[1,0,1]
	v_pk_fma_f32 v[10:11], v[134:135], v[250:251], v[10:11] op_sel_hi:[1,0,1]
	v_pk_fma_f32 v[8:9], v[132:133], v[250:251], v[8:9] op_sel_hi:[1,0,1]
	v_pk_fma_f32 v[6:7], v[134:135], v[82:83], v[6:7] op_sel_hi:[1,0,1]
	v_pk_fma_f32 v[4:5], v[132:133], v[82:83], v[4:5] op_sel_hi:[1,0,1]
	v_pk_fma_f32 v[2:3], v[134:135], v[74:75], v[2:3] op_sel_hi:[1,0,1]
	v_pk_fma_f32 v[0:1], v[132:133], v[74:75], v[0:1] op_sel_hi:[1,0,1]
	ds_read2st64_b32 v[244:245], v49 offset1:8
	ds_read2st64_b32 v[246:247], v49 offset0:16 offset1:24
	ds_read2st64_b32 v[248:249], v49 offset0:32 offset1:40
	ds_read2st64_b32 v[250:251], v49 offset0:48 offset1:56
	ds_read_b32 v74, v49 offset:16384
	v_add_u32_e32 v49, 64, v49
	s_waitcnt lgkmcnt(5)
	v_mov_b32_e32 v66, v57
	v_mov_b32_e32 v68, v59
	v_mov_b32_e32 v70, v61
	v_mov_b32_e32 v72, v63
	s_waitcnt vmcnt(19)
	v_pk_fma_f32 v[34:35], v[138:139], v[56:57], v[34:35] op_sel_hi:[1,0,1]
	v_pk_fma_f32 v[32:33], v[136:137], v[56:57], v[32:33] op_sel_hi:[1,0,1]
	v_pk_fma_f32 v[30:31], v[138:139], v[66:67], v[30:31] op_sel_hi:[1,0,1]
	v_pk_fma_f32 v[28:29], v[136:137], v[66:67], v[28:29] op_sel_hi:[1,0,1]
	v_pk_fma_f32 v[26:27], v[138:139], v[58:59], v[26:27] op_sel_hi:[1,0,1]
	v_pk_fma_f32 v[24:25], v[136:137], v[58:59], v[24:25] op_sel_hi:[1,0,1]
	v_pk_fma_f32 v[22:23], v[138:139], v[68:69], v[22:23] op_sel_hi:[1,0,1]
	v_pk_fma_f32 v[20:21], v[136:137], v[68:69], v[20:21] op_sel_hi:[1,0,1]
	v_pk_fma_f32 v[18:19], v[138:139], v[60:61], v[18:19] op_sel_hi:[1,0,1]
	v_pk_fma_f32 v[16:17], v[136:137], v[60:61], v[16:17] op_sel_hi:[1,0,1]
	v_pk_fma_f32 v[14:15], v[138:139], v[70:71], v[14:15] op_sel_hi:[1,0,1]
	v_pk_fma_f32 v[12:13], v[136:137], v[70:71], v[12:13] op_sel_hi:[1,0,1]
	v_pk_fma_f32 v[10:11], v[138:139], v[62:63], v[10:11] op_sel_hi:[1,0,1]
	v_pk_fma_f32 v[8:9], v[136:137], v[62:63], v[8:9] op_sel_hi:[1,0,1]
	v_pk_fma_f32 v[6:7], v[138:139], v[72:73], v[6:7] op_sel_hi:[1,0,1]
	v_pk_fma_f32 v[4:5], v[136:137], v[72:73], v[4:5] op_sel_hi:[1,0,1]
	v_pk_fma_f32 v[2:3], v[138:139], v[64:65], v[2:3] op_sel_hi:[1,0,1]
	v_pk_fma_f32 v[0:1], v[136:137], v[64:65], v[0:1] op_sel_hi:[1,0,1]
	ds_read2st64_b32 v[56:57], v49 offset1:8
	ds_read2st64_b32 v[58:59], v49 offset0:16 offset1:24
	ds_read2st64_b32 v[60:61], v49 offset0:32 offset1:40
	ds_read2st64_b32 v[62:63], v49 offset0:48 offset1:56
	ds_read_b32 v64, v49 offset:16384
	v_add_u32_e32 v49, 64, v49
	s_waitcnt lgkmcnt(5)
	v_mov_b32_e32 v76, v245
	v_mov_b32_e32 v78, v247
	v_mov_b32_e32 v80, v249
	v_mov_b32_e32 v82, v251
	s_waitcnt vmcnt(18)
; __device__ __forceinline__ void phase_prep(const Params& p, LAS unsigned char* lds, bool do_mod) {
;     ...
;         for (int kk = kr; kk < 512; kk += 16) {
;             const f32x4 w = *(const f32x4*)(p.w_mod + (size_t)(ks * 512 + kk) * MODW + cb * 128 + c4 * 4);
; #pragma unroll
;             for (int b = 0; b < 9; ++b) a[b] += w * sv[b * 512 + kk];
;         }
	v_pk_fma_f32 v[34:35], v[142:143], v[244:245], v[34:35] op_sel_hi:[1,0,1]
	v_pk_fma_f32 v[32:33], v[140:141], v[244:245], v[32:33] op_sel_hi:[1,0,1]
	v_pk_fma_f32 v[30:31], v[142:143], v[76:77], v[30:31] op_sel_hi:[1,0,1]
	v_pk_fma_f32 v[28:29], v[140:141], v[76:77], v[28:29] op_sel_hi:[1,0,1]
	v_pk_fma_f32 v[26:27], v[142:143], v[246:247], v[26:27] op_sel_hi:[1,0,1]
	v_pk_fma_f32 v[24:25], v[140:141], v[246:247], v[24:25] op_sel_hi:[1,0,1]
	v_pk_fma_f32 v[22:23], v[142:143], v[78:79], v[22:23] op_sel_hi:[1,0,1]
	v_pk_fma_f32 v[20:21], v[140:141], v[78:79], v[20:21] op_sel_hi:[1,0,1]
	v_pk_fma_f32 v[18:19], v[142:143], v[248:249], v[18:19] op_sel_hi:[1,0,1]
	v_pk_fma_f32 v[16:17], v[140:141], v[248:249], v[16:17] op_sel_hi:[1,0,1]
	v_pk_fma_f32 v[14:15], v[142:143], v[80:81], v[14:15] op_sel_hi:[1,0,1]
	v_pk_fma_f32 v[12:13], v[140:141], v[80:81], v[12:13] op_sel_hi:[1,0,1]
	v_pk_fma_f32 v[10:11], v[142:143], v[250:251], v[10:11] op_sel_hi:[1,0,1]
	v_pk_fma_f32 v[8:9], v[140:141], v[250:251], v[8:9] op_sel_hi:[1,0,1]
	v_pk_fma_f32 v[6:7], v[142:143], v[82:83], v[6:7] op_sel_hi:[1,0,1]
	v_pk_fma_f32 v[4:5], v[140:141], v[82:83], v[4:5] op_sel_hi:[1,0,1]
	v_pk_fma_f32 v[2:3], v[142:143], v[74:75], v[2:3] op_sel_hi:[1,0,1]
	v_pk_fma_f32 v[0:1], v[140:141], v[74:75], v[0:1] op_sel_hi:[1,0,1]
	ds_read2st64_b32 v[244:245], v49 offset1:8
	ds_read2st64_b32 v[246:247], v49 offset0:16 offset1:24
	ds_read2st64_b32 v[248:249], v49 offset0:32 offset1:40
	ds_read2st64_b32 v[250:251], v49 offset0:48 offset1:56
	ds_read_b32 v74, v49 offset:16384
	v_add_u32_e32 v49, 64, v49
	s_waitcnt lgkmcnt(5)
	v_mov_b32_e32 v66, v57
	v_mov_b32_e32 v68, v59
	v_mov_b32_e32 v70, v61
	v_mov_b32_e32 v72, v63
	s_waitcnt vmcnt(17)
	v_pk_fma_f32 v[34:35], v[146:147], v[56:57], v[34:35] op_sel_hi:[1,0,1]
	v_pk_fma_f32 v[32:33], v[144:145], v[56:57], v[32:33] op_sel_hi:[1,0,1]
	v_pk_fma_f32 v[30:31], v[146:147], v[66:67], v[30:31] op_sel_hi:[1,0,1]
	v_pk_fma_f32 v[28:29], v[144:145], v[66:67], v[28:29] op_sel_hi:[1,0,1]
	v_pk_fma_f32 v[26:27], v[146:147], v[58:59], v[26:27] op_sel_hi:[1,0,1]
	v_pk_fma_f32 v[24:25], v[144:145], v[58:59], v[24:25] op_sel_hi:[1,0,1]
	v_pk_fma_f32 v[22:23], v[146:147], v[68:69], v[22:23] op_sel_hi:[1,0,1]
	v_pk_fma_f32 v[20:21], v[144:145], v[68:69], v[20:21] op_sel_hi:[1,0,1]
	v_pk_fma_f32 v[18:19], v[146:147], v[60:61], v[18:19] op_sel_hi:[1,0,1]
	v_pk_fma_f32 v[16:17], v[144:145], v[60:61], v[16:17] op_sel_hi:[1,0,1]
	v_pk_fma_f32 v[14:15], v[146:147], v[70:71], v[14:15] op_sel_hi:[1,0,1]
	v_pk_fma_f32 v[12:13], v[144:145], v[70:71], v[12:13] op_sel_hi:[1,0,1]
	v_pk_fma_f32 v[10:11], v[146:147], v[62:63], v[10:11] op_sel_hi:[1,0,1]
	v_pk_fma_f32 v[8:9], v[144:145], v[62:63], v[8:9] op_sel_hi:[1,0,1]
	v_pk_fma_f32 v[6:7], v[146:147], v[72:73], v[6:7] op_sel_hi:[1,0,1]
	v_pk_fma_f32 v[4:5], v[144:145], v[72:73], v[4:5] op_sel_hi:[1,0,1]
	v_pk_fma_f32 v[2:3], v[146:147], v[64:65], v[2:3] op_sel_hi:[1,0,1]
	v_pk_fma_f32 v[0:1], v[144:145], v[64:65], v[0:1] op_sel_hi:[1,0,1]
	ds_read2st64_b32 v[56:57], v49 offset1:8
	ds_read2st64_b32 v[58:59], v49 offset0:16 offset1:24
	ds_read2st64_b32 v[60:61], v49 offset0:32 offset1:40
	ds_read2st64_b32 v[62:63], v49 offset0:48 offset1:56
	ds_read_b32 v64, v49 offset:16384
	v_add_u32_e32 v49, 64, v49
	s_waitcnt lgkmcnt(5)
	v_mov_b32_e32 v76, v245
	v_mov_b32_e32 v78, v247
	v_mov_b32_e32 v80, v249
	v_mov_b32_e32 v82, v251
	s_waitcnt vmcnt(16)
	v_pk_fma_f32 v[34:35], v[150:151], v[244:245], v[34:35] op_sel_hi:[1,0,1]
	v_pk_fma_f32 v[32:33], v[148:149], v[244:245], v[32:33] op_sel_hi:[1,0,1]
	v_pk_fma_f32 v[30:31], v[150:151], v[76:77], v[30:31] op_sel_hi:[1,0,1]
	v_pk_fma_f32 v[28:29], v[148:149], v[76:77], v[28:29] op_sel_hi:[1,0,1]
	v_pk_fma_f32 v[26:27], v[150:151], v[246:247], v[26:27] op_sel_hi:[1,0,1]
	v_pk_fma_f32 v[24:25], v[148:149], v[246:247], v[24:25] op_sel_hi:[1,0,1]
	v_pk_fma_f32 v[22:23], v[150:151], v[78:79], v[22:23] op_sel_hi:[1,0,1]
	v_pk_fma_f32 v[20:21], v[148:149], v[78:79], v[20:21] op_sel_hi:[1,0,1]
	v_pk_fma_f32 v[18:19], v[150:151], v[248:249], v[18:19] op_sel_hi:[1,0,1]
	v_pk_fma_f32 v[16:17], v[148:149], v[248:249], v[16:17] op_sel_hi:[1,0,1]
	v_pk_fma_f32 v[14:15], v[150:151], v[80:81], v[14:15] op_sel_hi:[1,0,1]
	v_pk_fma_f32 v[12:13], v[148:149], v[80:81], v[12:13] op_sel_hi:[1,0,1]
	v_pk_fma_f32 v[10:11], v[150:151], v[250:251], v[10:11] op_sel_hi:[1,0,1]
	v_pk_fma_f32 v[8:9], v[148:149], v[250:251], v[8:9] op_sel_hi:[1,0,1]
	v_pk_fma_f32 v[6:7], v[150:151], v[82:83], v[6:7] op_sel_hi:[1,0,1]
	v_pk_fma_f32 v[4:5], v[148:149], v[82:83], v[4:5] op_sel_hi:[1,0,1]
	v_pk_fma_f32 v[2:3], v[150:151], v[74:75], v[2:3] op_sel_hi:[1,0,1]
	v_pk_fma_f32 v[0:1], v[148:149], v[74:75], v[0:1] op_sel_hi:[1,0,1]
	ds_read2st64_b32 v[244:245], v49 offset1:8
	ds_read2st64_b32 v[246:247], v49 offset0:16 offset1:24
	ds_read2st64_b32 v[248:249], v49 offset0:32 offset1:40
	ds_read2st64_b32 v[250:251], v49 offset0:48 offset1:56
	ds_read_b32 v74, v49 offset:16384
	v_add_u32_e32 v49, 64, v49
	s_waitcnt lgkmcnt(5)
	v_mov_b32_e32 v66, v57
	v_mov_b32_e32 v68, v59
	v_mov_b32_e32 v70, v61
	v_mov_b32_e32 v72, v63
	s_waitcnt vmcnt(15)
; __device__ __forceinline__ void phase_prep(const Params& p, LAS unsigned char* lds, bool do_mod) {
;     ...
;         for (int kk = kr; kk < 512; kk += 16) {
;             const f32x4 w = *(const f32x4*)(p.w_mod + (size_t)(ks * 512 + kk) * MODW + cb * 128 + c4 * 4);
; #pragma unroll
;             for (int b = 0; b < 9; ++b) a[b] += w * sv[b * 512 + kk];
;         }
	v_pk_fma_f32 v[34:35], v[154:155], v[56:57], v[34:35] op_sel_hi:[1,0,1]
	v_pk_fma_f32 v[32:33], v[152:153], v[56:57], v[32:33] op_sel_hi:[1,0,1]
	v_pk_fma_f32 v[30:31], v[154:155], v[66:67], v[30:31] op_sel_hi:[1,0,1]
	v_pk_fma_f32 v[28:29], v[152:153], v[66:67], v[28:29] op_sel_hi:[1,0,1]
	v_pk_fma_f32 v[26:27], v[154:155], v[58:59], v[26:27] op_sel_hi:[1,0,1]
	v_pk_fma_f32 v[24:25], v[152:153], v[58:59], v[24:25] op_sel_hi:[1,0,1]
	v_pk_fma_f32 v[22:23], v[154:155], v[68:69], v[22:23] op_sel_hi:[1,0,1]
	v_pk_fma_f32 v[20:21], v[152:153], v[68:69], v[20:21] op_sel_hi:[1,0,1]
	v_pk_fma_f32 v[18:19], v[154:155], v[60:61], v[18:19] op_sel_hi:[1,0,1]
	v_pk_fma_f32 v[16:17], v[152:153], v[60:61], v[16:17] op_sel_hi:[1,0,1]
	v_pk_fma_f32 v[14:15], v[154:155], v[70:71], v[14:15] op_sel_hi:[1,0,1]
	v_pk_fma_f32 v[12:13], v[152:153], v[70:71], v[12:13] op_sel_hi:[1,0,1]
	v_pk_fma_f32 v[10:11], v[154:155], v[62:63], v[10:11] op_sel_hi:[1,0,1]
	v_pk_fma_f32 v[8:9], v[152:153], v[62:63], v[8:9] op_sel_hi:[1,0,1]
	v_pk_fma_f32 v[6:7], v[154:155], v[72:73], v[6:7] op_sel_hi:[1,0,1]
	v_pk_fma_f32 v[4:5], v[152:153], v[72:73], v[4:5] op_sel_hi:[1,0,1]
	v_pk_fma_f32 v[2:3], v[154:155], v[64:65], v[2:3] op_sel_hi:[1,0,1]
	v_pk_fma_f32 v[0:1], v[152:153], v[64:65], v[0:1] op_sel_hi:[1,0,1]
	ds_read2st64_b32 v[56:57], v49 offset1:8
	ds_read2st64_b32 v[58:59], v49 offset0:16 offset1:24
	ds_read2st64_b32 v[60:61], v49 offset0:32 offset1:40
	ds_read2st64_b32 v[62:63], v49 offset0:48 offset1:56
	ds_read_b32 v64, v49 offset:16384
	v_add_u32_e32 v49, 64, v49
	s_waitcnt lgkmcnt(5)
	v_mov_b32_e32 v76, v245
	v_mov_b32_e32 v78, v247
	v_mov_b32_e32 v80, v249
	v_mov_b32_e32 v82, v251
	s_waitcnt vmcnt(14)
	v_pk_fma_f32 v[34:35], v[158:159], v[244:245], v[34:35] op_sel_hi:[1,0,1]
	v_pk_fma_f32 v[32:33], v[156:157], v[244:245], v[32:33] op_sel_hi:[1,0,1]
	v_pk_fma_f32 v[30:31], v[158:159], v[76:77], v[30:31] op_sel_hi:[1,0,1]
	v_pk_fma_f32 v[28:29], v[156:157], v[76:77], v[28:29] op_sel_hi:[1,0,1]
	v_pk_fma_f32 v[26:27], v[158:159], v[246:247], v[26:27] op_sel_hi:[1,0,1]
	v_pk_fma_f32 v[24:25], v[156:157], v[246:247], v[24:25] op_sel_hi:[1,0,1]
	v_pk_fma_f32 v[22:23], v[158:159], v[78:79], v[22:23] op_sel_hi:[1,0,1]
	v_pk_fma_f32 v[20:21], v[156:157], v[78:79], v[20:21] op_sel_hi:[1,0,1]
	v_pk_fma_f32 v[18:19], v[158:159], v[248:249], v[18:19] op_sel_hi:[1,0,1]
	v_pk_fma_f32 v[16:17], v[156:157], v[248:249], v[16:17] op_sel_hi:[1,0,1]
	v_pk_fma_f32 v[14:15], v[158:159], v[80:81], v[14:15] op_sel_hi:[1,0,1]
	v_pk_fma_f32 v[12:13], v[156:157], v[80:81], v[12:13] op_sel_hi:[1,0,1]
	v_pk_fma_f32 v[10:11], v[158:159], v[250:251], v[10:11] op_sel_hi:[1,0,1]
	v_pk_fma_f32 v[8:9], v[156:157], v[250:251], v[8:9] op_sel_hi:[1,0,1]
	v_pk_fma_f32 v[6:7], v[158:159], v[82:83], v[6:7] op_sel_hi:[1,0,1]
	v_pk_fma_f32 v[4:5], v[156:157], v[82:83], v[4:5] op_sel_hi:[1,0,1]
	v_pk_fma_f32 v[2:3], v[158:159], v[74:75], v[2:3] op_sel_hi:[1,0,1]
	v_pk_fma_f32 v[0:1], v[156:157], v[74:75], v[0:1] op_sel_hi:[1,0,1]
	ds_read2st64_b32 v[244:245], v49 offset1:8
	ds_read2st64_b32 v[246:247], v49 offset0:16 offset1:24
	ds_read2st64_b32 v[248:249], v49 offset0:32 offset1:40
	ds_read2st64_b32 v[250:251], v49 offset0:48 offset1:56
	ds_read_b32 v74, v49 offset:16384
	v_add_u32_e32 v49, 64, v49
	s_waitcnt lgkmcnt(5)
	v_mov_b32_e32 v66, v57
	v_mov_b32_e32 v68, v59
	v_mov_b32_e32 v70, v61
	v_mov_b32_e32 v72, v63
	s_waitcnt vmcnt(13)
	v_pk_fma_f32 v[34:35], v[162:163], v[56:57], v[34:35] op_sel_hi:[1,0,1]
	v_pk_fma_f32 v[32:33], v[160:161], v[56:57], v[32:33] op_sel_hi:[1,0,1]
	v_pk_fma_f32 v[30:31], v[162:163], v[66:67], v[30:31] op_sel_hi:[1,0,1]
	v_pk_fma_f32 v[28:29], v[160:161], v[66:67], v[28:29] op_sel_hi:[1,0,1]
	v_pk_fma_f32 v[26:27], v[162:163], v[58:59], v[26:27] op_sel_hi:[1,0,1]
	v_pk_fma_f32 v[24:25], v[160:161], v[58:59], v[24:25] op_sel_hi:[1,0,1]
	v_pk_fma_f32 v[22:23], v[162:163], v[68:69], v[22:23] op_sel_hi:[1,0,1]
	v_pk_fma_f32 v[20:21], v[160:161], v[68:69], v[20:21] op_sel_hi:[1,0,1]
	v_pk_fma_f32 v[18:19], v[162:163], v[60:61], v[18:19] op_sel_hi:[1,0,1]
	v_pk_fma_f32 v[16:17], v[160:161], v[60:61], v[16:17] op_sel_hi:[1,0,1]
	v_pk_fma_f32 v[14:15], v[162:163], v[70:71], v[14:15] op_sel_hi:[1,0,1]
	v_pk_fma_f32 v[12:13], v[160:161], v[70:71], v[12:13] op_sel_hi:[1,0,1]
	v_pk_fma_f32 v[10:11], v[162:163], v[62:63], v[10:11] op_sel_hi:[1,0,1]
	v_pk_fma_f32 v[8:9], v[160:161], v[62:63], v[8:9] op_sel_hi:[1,0,1]
	v_pk_fma_f32 v[6:7], v[162:163], v[72:73], v[6:7] op_sel_hi:[1,0,1]
	v_pk_fma_f32 v[4:5], v[160:161], v[72:73], v[4:5] op_sel_hi:[1,0,1]
	v_pk_fma_f32 v[2:3], v[162:163], v[64:65], v[2:3] op_sel_hi:[1,0,1]
	v_pk_fma_f32 v[0:1], v[160:161], v[64:65], v[0:1] op_sel_hi:[1,0,1]
	ds_read2st64_b32 v[56:57], v49 offset1:8
	ds_read2st64_b32 v[58:59], v49 offset0:16 offset1:24
	ds_read2st64_b32 v[60:61], v49 offset0:32 offset1:40
	ds_read2st64_b32 v[62:63], v49 offset0:48 offset1:56
	ds_read_b32 v64, v49 offset:16384
	v_add_u32_e32 v49, 64, v49
	s_waitcnt lgkmcnt(5)
	v_mov_b32_e32 v76, v245
	v_mov_b32_e32 v78, v247
	v_mov_b32_e32 v80, v249
	v_mov_b32_e32 v82, v251
	s_waitcnt vmcnt(12)
; __device__ __forceinline__ void phase_prep(const Params& p, LAS unsigned char* lds, bool do_mod) {
;     ...
;         for (int kk = kr; kk < 512; kk += 16) {
;             const f32x4 w = *(const f32x4*)(p.w_mod + (size_t)(ks * 512 + kk) * MODW + cb * 128 + c4 * 4);
; #pragma unroll
;             for (int b = 0; b < 9; ++b) a[b] += w * sv[b * 512 + kk];
;         }
	v_pk_fma_f32 v[34:35], v[166:167], v[244:245], v[34:35] op_sel_hi:[1,0,1]
	v_pk_fma_f32 v[32:33], v[164:165], v[244:245], v[32:33] op_sel_hi:[1,0,1]
	v_pk_fma_f32 v[30:31], v[166:167], v[76:77], v[30:31] op_sel_hi:[1,0,1]
	v_pk_fma_f32 v[28:29], v[164:165], v[76:77], v[28:29] op_sel_hi:[1,0,1]
	v_pk_fma_f32 v[26:27], v[166:167], v[246:247], v[26:27] op_sel_hi:[1,0,1]
	v_pk_fma_f32 v[24:25], v[164:165], v[246:247], v[24:25] op_sel_hi:[1,0,1]
	v_pk_fma_f32 v[22:23], v[166:167], v[78:79], v[22:23] op_sel_hi:[1,0,1]
	v_pk_fma_f32 v[20:21], v[164:165], v[78:79], v[20:21] op_sel_hi:[1,0,1]
	v_pk_fma_f32 v[18:19], v[166:167], v[248:249], v[18:19] op_sel_hi:[1,0,1]
	v_pk_fma_f32 v[16:17], v[164:165], v[248:249], v[16:17] op_sel_hi:[1,0,1]
	v_pk_fma_f32 v[14:15], v[166:167], v[80:81], v[14:15] op_sel_hi:[1,0,1]
	v_pk_fma_f32 v[12:13], v[164:165], v[80:81], v[12:13] op_sel_hi:[1,0,1]
	v_pk_fma_f32 v[10:11], v[166:167], v[250:251], v[10:11] op_sel_hi:[1,0,1]
	v_pk_fma_f32 v[8:9], v[164:165], v[250:251], v[8:9] op_sel_hi:[1,0,1]
	v_pk_fma_f32 v[6:7], v[166:167], v[82:83], v[6:7] op_sel_hi:[1,0,1]
	v_pk_fma_f32 v[4:5], v[164:165], v[82:83], v[4:5] op_sel_hi:[1,0,1]
	v_pk_fma_f32 v[2:3], v[166:167], v[74:75], v[2:3] op_sel_hi:[1,0,1]
	v_pk_fma_f32 v[0:1], v[164:165], v[74:75], v[0:1] op_sel_hi:[1,0,1]
	ds_read2st64_b32 v[244:245], v49 offset1:8
	ds_read2st64_b32 v[246:247], v49 offset0:16 offset1:24
	ds_read2st64_b32 v[248:249], v49 offset0:32 offset1:40
	ds_read2st64_b32 v[250:251], v49 offset0:48 offset1:56
	ds_read_b32 v74, v49 offset:16384
	v_add_u32_e32 v49, 64, v49
	s_waitcnt lgkmcnt(5)
	v_mov_b32_e32 v66, v57
	v_mov_b32_e32 v68, v59
	v_mov_b32_e32 v70, v61
	v_mov_b32_e32 v72, v63
	s_waitcnt vmcnt(11)
	v_pk_fma_f32 v[34:35], v[170:171], v[56:57], v[34:35] op_sel_hi:[1,0,1]
	v_pk_fma_f32 v[32:33], v[168:169], v[56:57], v[32:33] op_sel_hi:[1,0,1]
	v_pk_fma_f32 v[30:31], v[170:171], v[66:67], v[30:31] op_sel_hi:[1,0,1]
	v_pk_fma_f32 v[28:29], v[168:169], v[66:67], v[28:29] op_sel_hi:[1,0,1]
	v_pk_fma_f32 v[26:27], v[170:171], v[58:59], v[26:27] op_sel_hi:[1,0,1]
	v_pk_fma_f32 v[24:25], v[168:169], v[58:59], v[24:25] op_sel_hi:[1,0,1]
	v_pk_fma_f32 v[22:23], v[170:171], v[68:69], v[22:23] op_sel_hi:[1,0,1]
	v_pk_fma_f32 v[20:21], v[168:169], v[68:69], v[20:21] op_sel_hi:[1,0,1]
	v_pk_fma_f32 v[18:19], v[170:171], v[60:61], v[18:19] op_sel_hi:[1,0,1]
	v_pk_fma_f32 v[16:17], v[168:169], v[60:61], v[16:17] op_sel_hi:[1,0,1]
	v_pk_fma_f32 v[14:15], v[170:171], v[70:71], v[14:15] op_sel_hi:[1,0,1]
	v_pk_fma_f32 v[12:13], v[168:169], v[70:71], v[12:13] op_sel_hi:[1,0,1]
	v_pk_fma_f32 v[10:11], v[170:171], v[62:63], v[10:11] op_sel_hi:[1,0,1]
	v_pk_fma_f32 v[8:9], v[168:169], v[62:63], v[8:9] op_sel_hi:[1,0,1]
	v_pk_fma_f32 v[6:7], v[170:171], v[72:73], v[6:7] op_sel_hi:[1,0,1]
	v_pk_fma_f32 v[4:5], v[168:169], v[72:73], v[4:5] op_sel_hi:[1,0,1]
	v_pk_fma_f32 v[2:3], v[170:171], v[64:65], v[2:3] op_sel_hi:[1,0,1]
	v_pk_fma_f32 v[0:1], v[168:169], v[64:65], v[0:1] op_sel_hi:[1,0,1]
	ds_read2st64_b32 v[56:57], v49 offset1:8
	ds_read2st64_b32 v[58:59], v49 offset0:16 offset1:24
	ds_read2st64_b32 v[60:61], v49 offset0:32 offset1:40
	ds_read2st64_b32 v[62:63], v49 offset0:48 offset1:56
	ds_read_b32 v64, v49 offset:16384
	v_add_u32_e32 v49, 64, v49
	s_waitcnt lgkmcnt(5)
	v_mov_b32_e32 v76, v245
	v_mov_b32_e32 v78, v247
	v_mov_b32_e32 v80, v249
	v_mov_b32_e32 v82, v251
	s_waitcnt vmcnt(10)
	v_pk_fma_f32 v[34:35], v[174:175], v[244:245], v[34:35] op_sel_hi:[1,0,1]
	v_pk_fma_f32 v[32:33], v[172:173], v[244:245], v[32:33] op_sel_hi:[1,0,1]
	v_pk_fma_f32 v[30:31], v[174:175], v[76:77], v[30:31] op_sel_hi:[1,0,1]
	v_pk_fma_f32 v[28:29], v[172:173], v[76:77], v[28:29] op_sel_hi:[1,0,1]
	v_pk_fma_f32 v[26:27], v[174:175], v[246:247], v[26:27] op_sel_hi:[1,0,1]
	v_pk_fma_f32 v[24:25], v[172:173], v[246:247], v[24:25] op_sel_hi:[1,0,1]
	v_pk_fma_f32 v[22:23], v[174:175], v[78:79], v[22:23] op_sel_hi:[1,0,1]
	v_pk_fma_f32 v[20:21], v[172:173], v[78:79], v[20:21] op_sel_hi:[1,0,1]
	v_pk_fma_f32 v[18:19], v[174:175], v[248:249], v[18:19] op_sel_hi:[1,0,1]
	v_pk_fma_f32 v[16:17], v[172:173], v[248:249], v[16:17] op_sel_hi:[1,0,1]
	v_pk_fma_f32 v[14:15], v[174:175], v[80:81], v[14:15] op_sel_hi:[1,0,1]
	v_pk_fma_f32 v[12:13], v[172:173], v[80:81], v[12:13] op_sel_hi:[1,0,1]
	v_pk_fma_f32 v[10:11], v[174:175], v[250:251], v[10:11] op_sel_hi:[1,0,1]
	v_pk_fma_f32 v[8:9], v[172:173], v[250:251], v[8:9] op_sel_hi:[1,0,1]
	v_pk_fma_f32 v[6:7], v[174:175], v[82:83], v[6:7] op_sel_hi:[1,0,1]
	v_pk_fma_f32 v[4:5], v[172:173], v[82:83], v[4:5] op_sel_hi:[1,0,1]
	v_pk_fma_f32 v[2:3], v[174:175], v[74:75], v[2:3] op_sel_hi:[1,0,1]
	v_pk_fma_f32 v[0:1], v[172:173], v[74:75], v[0:1] op_sel_hi:[1,0,1]
	ds_read2st64_b32 v[244:245], v49 offset1:8
	ds_read2st64_b32 v[246:247], v49 offset0:16 offset1:24
	ds_read2st64_b32 v[248:249], v49 offset0:32 offset1:40
	ds_read2st64_b32 v[250:251], v49 offset0:48 offset1:56
	ds_read_b32 v74, v49 offset:16384
	v_add_u32_e32 v49, 64, v49
	s_waitcnt lgkmcnt(5)
	v_mov_b32_e32 v66, v57
	v_mov_b32_e32 v68, v59
	v_mov_b32_e32 v70, v61
	v_mov_b32_e32 v72, v63
	s_waitcnt vmcnt(9)
; __device__ __forceinline__ void phase_prep(const Params& p, LAS unsigned char* lds, bool do_mod) {
;     ...
;         for (int kk = kr; kk < 512; kk += 16) {
;             const f32x4 w = *(const f32x4*)(p.w_mod + (size_t)(ks * 512 + kk) * MODW + cb * 128 + c4 * 4);
; #pragma unroll
;             for (int b = 0; b < 9; ++b) a[b] += w * sv[b * 512 + kk];
;         }
	v_pk_fma_f32 v[34:35], v[214:215], v[56:57], v[34:35] op_sel_hi:[1,0,1]
	v_pk_fma_f32 v[32:33], v[212:213], v[56:57], v[32:33] op_sel_hi:[1,0,1]
	v_pk_fma_f32 v[30:31], v[214:215], v[66:67], v[30:31] op_sel_hi:[1,0,1]
	v_pk_fma_f32 v[28:29], v[212:213], v[66:67], v[28:29] op_sel_hi:[1,0,1]
	v_pk_fma_f32 v[26:27], v[214:215], v[58:59], v[26:27] op_sel_hi:[1,0,1]
	v_pk_fma_f32 v[24:25], v[212:213], v[58:59], v[24:25] op_sel_hi:[1,0,1]
	v_pk_fma_f32 v[22:23], v[214:215], v[68:69], v[22:23] op_sel_hi:[1,0,1]
	v_pk_fma_f32 v[20:21], v[212:213], v[68:69], v[20:21] op_sel_hi:[1,0,1]
	v_pk_fma_f32 v[18:19], v[214:215], v[60:61], v[18:19] op_sel_hi:[1,0,1]
	v_pk_fma_f32 v[16:17], v[212:213], v[60:61], v[16:17] op_sel_hi:[1,0,1]
	v_pk_fma_f32 v[14:15], v[214:215], v[70:71], v[14:15] op_sel_hi:[1,0,1]
	v_pk_fma_f32 v[12:13], v[212:213], v[70:71], v[12:13] op_sel_hi:[1,0,1]
	v_pk_fma_f32 v[10:11], v[214:215], v[62:63], v[10:11] op_sel_hi:[1,0,1]
	v_pk_fma_f32 v[8:9], v[212:213], v[62:63], v[8:9] op_sel_hi:[1,0,1]
	v_pk_fma_f32 v[6:7], v[214:215], v[72:73], v[6:7] op_sel_hi:[1,0,1]
	v_pk_fma_f32 v[4:5], v[212:213], v[72:73], v[4:5] op_sel_hi:[1,0,1]
	v_pk_fma_f32 v[2:3], v[214:215], v[64:65], v[2:3] op_sel_hi:[1,0,1]
	v_pk_fma_f32 v[0:1], v[212:213], v[64:65], v[0:1] op_sel_hi:[1,0,1]
	ds_read2st64_b32 v[56:57], v49 offset1:8
	ds_read2st64_b32 v[58:59], v49 offset0:16 offset1:24
	ds_read2st64_b32 v[60:61], v49 offset0:32 offset1:40
	ds_read2st64_b32 v[62:63], v49 offset0:48 offset1:56
	ds_read_b32 v64, v49 offset:16384
	v_add_u32_e32 v49, 64, v49
	s_waitcnt lgkmcnt(5)
	v_mov_b32_e32 v76, v245
	v_mov_b32_e32 v78, v247
	v_mov_b32_e32 v80, v249
	v_mov_b32_e32 v82, v251
	s_waitcnt vmcnt(8)
	v_pk_fma_f32 v[34:35], v[218:219], v[244:245], v[34:35] op_sel_hi:[1,0,1]
	v_pk_fma_f32 v[32:33], v[216:217], v[244:245], v[32:33] op_sel_hi:[1,0,1]
	v_pk_fma_f32 v[30:31], v[218:219], v[76:77], v[30:31] op_sel_hi:[1,0,1]
	v_pk_fma_f32 v[28:29], v[216:217], v[76:77], v[28:29] op_sel_hi:[1,0,1]
	v_pk_fma_f32 v[26:27], v[218:219], v[246:247], v[26:27] op_sel_hi:[1,0,1]
	v_pk_fma_f32 v[24:25], v[216:217], v[246:247], v[24:25] op_sel_hi:[1,0,1]
	v_pk_fma_f32 v[22:23], v[218:219], v[78:79], v[22:23] op_sel_hi:[1,0,1]
	v_pk_fma_f32 v[20:21], v[216:217], v[78:79], v[20:21] op_sel_hi:[1,0,1]
	v_pk_fma_f32 v[18:19], v[218:219], v[248:249], v[18:19] op_sel_hi:[1,0,1]
	v_pk_fma_f32 v[16:17], v[216:217], v[248:249], v[16:17] op_sel_hi:[1,0,1]
	v_pk_fma_f32 v[14:15], v[218:219], v[80:81], v[14:15] op_sel_hi:[1,0,1]
	v_pk_fma_f32 v[12:13], v[216:217], v[80:81], v[12:13] op_sel_hi:[1,0,1]
	v_pk_fma_f32 v[10:11], v[218:219], v[250:251], v[10:11] op_sel_hi:[1,0,1]
	v_pk_fma_f32 v[8:9], v[216:217], v[250:251], v[8:9] op_sel_hi:[1,0,1]
	v_pk_fma_f32 v[6:7], v[218:219], v[82:83], v[6:7] op_sel_hi:[1,0,1]
	v_pk_fma_f32 v[4:5], v[216:217], v[82:83], v[4:5] op_sel_hi:[1,0,1]
	v_pk_fma_f32 v[2:3], v[218:219], v[74:75], v[2:3] op_sel_hi:[1,0,1]
	v_pk_fma_f32 v[0:1], v[216:217], v[74:75], v[0:1] op_sel_hi:[1,0,1]
	ds_read2st64_b32 v[244:245], v49 offset1:8
	ds_read2st64_b32 v[246:247], v49 offset0:16 offset1:24
	ds_read2st64_b32 v[248:249], v49 offset0:32 offset1:40
	ds_read2st64_b32 v[250:251], v49 offset0:48 offset1:56
	ds_read_b32 v74, v49 offset:16384
	v_add_u32_e32 v49, 64, v49
	s_waitcnt lgkmcnt(5)
	v_mov_b32_e32 v66, v57
	v_mov_b32_e32 v68, v59
	v_mov_b32_e32 v70, v61
	v_mov_b32_e32 v72, v63
	s_waitcnt vmcnt(7)
	v_pk_fma_f32 v[34:35], v[222:223], v[56:57], v[34:35] op_sel_hi:[1,0,1]
	v_pk_fma_f32 v[32:33], v[220:221], v[56:57], v[32:33] op_sel_hi:[1,0,1]
	v_pk_fma_f32 v[30:31], v[222:223], v[66:67], v[30:31] op_sel_hi:[1,0,1]
	v_pk_fma_f32 v[28:29], v[220:221], v[66:67], v[28:29] op_sel_hi:[1,0,1]
	v_pk_fma_f32 v[26:27], v[222:223], v[58:59], v[26:27] op_sel_hi:[1,0,1]
	v_pk_fma_f32 v[24:25], v[220:221], v[58:59], v[24:25] op_sel_hi:[1,0,1]
	v_pk_fma_f32 v[22:23], v[222:223], v[68:69], v[22:23] op_sel_hi:[1,0,1]
	v_pk_fma_f32 v[20:21], v[220:221], v[68:69], v[20:21] op_sel_hi:[1,0,1]
	v_pk_fma_f32 v[18:19], v[222:223], v[60:61], v[18:19] op_sel_hi:[1,0,1]
	v_pk_fma_f32 v[16:17], v[220:221], v[60:61], v[16:17] op_sel_hi:[1,0,1]
	v_pk_fma_f32 v[14:15], v[222:223], v[70:71], v[14:15] op_sel_hi:[1,0,1]
	v_pk_fma_f32 v[12:13], v[220:221], v[70:71], v[12:13] op_sel_hi:[1,0,1]
	v_pk_fma_f32 v[10:11], v[222:223], v[62:63], v[10:11] op_sel_hi:[1,0,1]
	v_pk_fma_f32 v[8:9], v[220:221], v[62:63], v[8:9] op_sel_hi:[1,0,1]
	v_pk_fma_f32 v[6:7], v[222:223], v[72:73], v[6:7] op_sel_hi:[1,0,1]
	v_pk_fma_f32 v[4:5], v[220:221], v[72:73], v[4:5] op_sel_hi:[1,0,1]
	v_pk_fma_f32 v[2:3], v[222:223], v[64:65], v[2:3] op_sel_hi:[1,0,1]
	v_pk_fma_f32 v[0:1], v[220:221], v[64:65], v[0:1] op_sel_hi:[1,0,1]
	ds_read2st64_b32 v[56:57], v49 offset1:8
	ds_read2st64_b32 v[58:59], v49 offset0:16 offset1:24
	ds_read2st64_b32 v[60:61], v49 offset0:32 offset1:40
	ds_read2st64_b32 v[62:63], v49 offset0:48 offset1:56
	ds_read_b32 v64, v49 offset:16384
	v_add_u32_e32 v49, 64, v49
	s_waitcnt lgkmcnt(5)
	v_mov_b32_e32 v76, v245
	v_mov_b32_e32 v78, v247
	v_mov_b32_e32 v80, v249
	v_mov_b32_e32 v82, v251
	s_waitcnt vmcnt(6)
; __device__ __forceinline__ void phase_prep(const Params& p, LAS unsigned char* lds, bool do_mod) {
;     ...
;         for (int kk = kr; kk < 512; kk += 16) {
;             const f32x4 w = *(const f32x4*)(p.w_mod + (size_t)(ks * 512 + kk) * MODW + cb * 128 + c4 * 4);
; #pragma unroll
;             for (int b = 0; b < 9; ++b) a[b] += w * sv[b * 512 + kk];
;         }
	v_pk_fma_f32 v[34:35], v[226:227], v[244:245], v[34:35] op_sel_hi:[1,0,1]
	v_pk_fma_f32 v[32:33], v[224:225], v[244:245], v[32:33] op_sel_hi:[1,0,1]
	v_pk_fma_f32 v[30:31], v[226:227], v[76:77], v[30:31] op_sel_hi:[1,0,1]
	v_pk_fma_f32 v[28:29], v[224:225], v[76:77], v[28:29] op_sel_hi:[1,0,1]
	v_pk_fma_f32 v[26:27], v[226:227], v[246:247], v[26:27] op_sel_hi:[1,0,1]
	v_pk_fma_f32 v[24:25], v[224:225], v[246:247], v[24:25] op_sel_hi:[1,0,1]
	v_pk_fma_f32 v[22:23], v[226:227], v[78:79], v[22:23] op_sel_hi:[1,0,1]
	v_pk_fma_f32 v[20:21], v[224:225], v[78:79], v[20:21] op_sel_hi:[1,0,1]
	v_pk_fma_f32 v[18:19], v[226:227], v[248:249], v[18:19] op_sel_hi:[1,0,1]
	v_pk_fma_f32 v[16:17], v[224:225], v[248:249], v[16:17] op_sel_hi:[1,0,1]
	v_pk_fma_f32 v[14:15], v[226:227], v[80:81], v[14:15] op_sel_hi:[1,0,1]
	v_pk_fma_f32 v[12:13], v[224:225], v[80:81], v[12:13] op_sel_hi:[1,0,1]
	v_pk_fma_f32 v[10:11], v[226:227], v[250:251], v[10:11] op_sel_hi:[1,0,1]
	v_pk_fma_f32 v[8:9], v[224:225], v[250:251], v[8:9] op_sel_hi:[1,0,1]
	v_pk_fma_f32 v[6:7], v[226:227], v[82:83], v[6:7] op_sel_hi:[1,0,1]
	v_pk_fma_f32 v[4:5], v[224:225], v[82:83], v[4:5] op_sel_hi:[1,0,1]
	v_pk_fma_f32 v[2:3], v[226:227], v[74:75], v[2:3] op_sel_hi:[1,0,1]
	v_pk_fma_f32 v[0:1], v[224:225], v[74:75], v[0:1] op_sel_hi:[1,0,1]
	ds_read2st64_b32 v[244:245], v49 offset1:8
	ds_read2st64_b32 v[246:247], v49 offset0:16 offset1:24
	ds_read2st64_b32 v[248:249], v49 offset0:32 offset1:40
	ds_read2st64_b32 v[250:251], v49 offset0:48 offset1:56
	ds_read_b32 v74, v49 offset:16384
	v_add_u32_e32 v49, 64, v49
	s_waitcnt lgkmcnt(5)
	v_mov_b32_e32 v66, v57
	v_mov_b32_e32 v68, v59
	v_mov_b32_e32 v70, v61
	v_mov_b32_e32 v72, v63
	s_waitcnt vmcnt(5)
	v_pk_fma_f32 v[34:35], v[230:231], v[56:57], v[34:35] op_sel_hi:[1,0,1]
	v_pk_fma_f32 v[32:33], v[228:229], v[56:57], v[32:33] op_sel_hi:[1,0,1]
	v_pk_fma_f32 v[30:31], v[230:231], v[66:67], v[30:31] op_sel_hi:[1,0,1]
	v_pk_fma_f32 v[28:29], v[228:229], v[66:67], v[28:29] op_sel_hi:[1,0,1]
	v_pk_fma_f32 v[26:27], v[230:231], v[58:59], v[26:27] op_sel_hi:[1,0,1]
	v_pk_fma_f32 v[24:25], v[228:229], v[58:59], v[24:25] op_sel_hi:[1,0,1]
	v_pk_fma_f32 v[22:23], v[230:231], v[68:69], v[22:23] op_sel_hi:[1,0,1]
	v_pk_fma_f32 v[20:21], v[228:229], v[68:69], v[20:21] op_sel_hi:[1,0,1]
	v_pk_fma_f32 v[18:19], v[230:231], v[60:61], v[18:19] op_sel_hi:[1,0,1]
	v_pk_fma_f32 v[16:17], v[228:229], v[60:61], v[16:17] op_sel_hi:[1,0,1]
	v_pk_fma_f32 v[14:15], v[230:231], v[70:71], v[14:15] op_sel_hi:[1,0,1]
	v_pk_fma_f32 v[12:13], v[228:229], v[70:71], v[12:13] op_sel_hi:[1,0,1]
	v_pk_fma_f32 v[10:11], v[230:231], v[62:63], v[10:11] op_sel_hi:[1,0,1]
	v_pk_fma_f32 v[8:9], v[228:229], v[62:63], v[8:9] op_sel_hi:[1,0,1]
	v_pk_fma_f32 v[6:7], v[230:231], v[72:73], v[6:7] op_sel_hi:[1,0,1]
	v_pk_fma_f32 v[4:5], v[228:229], v[72:73], v[4:5] op_sel_hi:[1,0,1]
	v_pk_fma_f32 v[2:3], v[230:231], v[64:65], v[2:3] op_sel_hi:[1,0,1]
	v_pk_fma_f32 v[0:1], v[228:229], v[64:65], v[0:1] op_sel_hi:[1,0,1]
	ds_read2st64_b32 v[56:57], v49 offset1:8
	ds_read2st64_b32 v[58:59], v49 offset0:16 offset1:24
	ds_read2st64_b32 v[60:61], v49 offset0:32 offset1:40
	ds_read2st64_b32 v[62:63], v49 offset0:48 offset1:56
	ds_read_b32 v64, v49 offset:16384
	v_add_u32_e32 v49, 64, v49
	s_waitcnt lgkmcnt(5)
	v_mov_b32_e32 v76, v245
	v_mov_b32_e32 v78, v247
	v_mov_b32_e32 v80, v249
	v_mov_b32_e32 v82, v251
	s_waitcnt vmcnt(4)
	v_pk_fma_f32 v[34:35], v[234:235], v[244:245], v[34:35] op_sel_hi:[1,0,1]
	v_pk_fma_f32 v[32:33], v[232:233], v[244:245], v[32:33] op_sel_hi:[1,0,1]
	v_pk_fma_f32 v[30:31], v[234:235], v[76:77], v[30:31] op_sel_hi:[1,0,1]
	v_pk_fma_f32 v[28:29], v[232:233], v[76:77], v[28:29] op_sel_hi:[1,0,1]
	v_pk_fma_f32 v[26:27], v[234:235], v[246:247], v[26:27] op_sel_hi:[1,0,1]
	v_pk_fma_f32 v[24:25], v[232:233], v[246:247], v[24:25] op_sel_hi:[1,0,1]
	v_pk_fma_f32 v[22:23], v[234:235], v[78:79], v[22:23] op_sel_hi:[1,0,1]
	v_pk_fma_f32 v[20:21], v[232:233], v[78:79], v[20:21] op_sel_hi:[1,0,1]
	v_pk_fma_f32 v[18:19], v[234:235], v[248:249], v[18:19] op_sel_hi:[1,0,1]
	v_pk_fma_f32 v[16:17], v[232:233], v[248:249], v[16:17] op_sel_hi:[1,0,1]
	v_pk_fma_f32 v[14:15], v[234:235], v[80:81], v[14:15] op_sel_hi:[1,0,1]
	v_pk_fma_f32 v[12:13], v[232:233], v[80:81], v[12:13] op_sel_hi:[1,0,1]
	v_pk_fma_f32 v[10:11], v[234:235], v[250:251], v[10:11] op_sel_hi:[1,0,1]
	v_pk_fma_f32 v[8:9], v[232:233], v[250:251], v[8:9] op_sel_hi:[1,0,1]
	v_pk_fma_f32 v[6:7], v[234:235], v[82:83], v[6:7] op_sel_hi:[1,0,1]
	v_pk_fma_f32 v[4:5], v[232:233], v[82:83], v[4:5] op_sel_hi:[1,0,1]
	v_pk_fma_f32 v[2:3], v[234:235], v[74:75], v[2:3] op_sel_hi:[1,0,1]
	v_pk_fma_f32 v[0:1], v[232:233], v[74:75], v[0:1] op_sel_hi:[1,0,1]
	ds_read2st64_b32 v[244:245], v49 offset1:8
	ds_read2st64_b32 v[246:247], v49 offset0:16 offset1:24
	ds_read2st64_b32 v[248:249], v49 offset0:32 offset1:40
	ds_read2st64_b32 v[250:251], v49 offset0:48 offset1:56
	ds_read_b32 v74, v49 offset:16384
	v_add_u32_e32 v49, 64, v49
	s_waitcnt lgkmcnt(5)
	v_mov_b32_e32 v66, v57
	v_mov_b32_e32 v68, v59
	v_mov_b32_e32 v70, v61
	v_mov_b32_e32 v72, v63
	s_waitcnt vmcnt(3)
; __device__ __forceinline__ void phase_prep(const Params& p, LAS unsigned char* lds, bool do_mod) {
;     ...
;         for (int kk = kr; kk < 512; kk += 16) {
;             const f32x4 w = *(const f32x4*)(p.w_mod + (size_t)(ks * 512 + kk) * MODW + cb * 128 + c4 * 4);
; #pragma unroll
;             for (int b = 0; b < 9; ++b) a[b] += w * sv[b * 512 + kk];
;         }
	v_pk_fma_f32 v[34:35], v[238:239], v[56:57], v[34:35] op_sel_hi:[1,0,1]
	v_pk_fma_f32 v[32:33], v[236:237], v[56:57], v[32:33] op_sel_hi:[1,0,1]
	v_pk_fma_f32 v[30:31], v[238:239], v[66:67], v[30:31] op_sel_hi:[1,0,1]
	v_pk_fma_f32 v[28:29], v[236:237], v[66:67], v[28:29] op_sel_hi:[1,0,1]
	v_pk_fma_f32 v[26:27], v[238:239], v[58:59], v[26:27] op_sel_hi:[1,0,1]
	v_pk_fma_f32 v[24:25], v[236:237], v[58:59], v[24:25] op_sel_hi:[1,0,1]
	v_pk_fma_f32 v[22:23], v[238:239], v[68:69], v[22:23] op_sel_hi:[1,0,1]
	v_pk_fma_f32 v[20:21], v[236:237], v[68:69], v[20:21] op_sel_hi:[1,0,1]
	v_pk_fma_f32 v[18:19], v[238:239], v[60:61], v[18:19] op_sel_hi:[1,0,1]
	v_pk_fma_f32 v[16:17], v[236:237], v[60:61], v[16:17] op_sel_hi:[1,0,1]
	v_pk_fma_f32 v[14:15], v[238:239], v[70:71], v[14:15] op_sel_hi:[1,0,1]
	v_pk_fma_f32 v[12:13], v[236:237], v[70:71], v[12:13] op_sel_hi:[1,0,1]
	v_pk_fma_f32 v[10:11], v[238:239], v[62:63], v[10:11] op_sel_hi:[1,0,1]
	v_pk_fma_f32 v[8:9], v[236:237], v[62:63], v[8:9] op_sel_hi:[1,0,1]
	v_pk_fma_f32 v[6:7], v[238:239], v[72:73], v[6:7] op_sel_hi:[1,0,1]
	v_pk_fma_f32 v[4:5], v[236:237], v[72:73], v[4:5] op_sel_hi:[1,0,1]
	v_pk_fma_f32 v[2:3], v[238:239], v[64:65], v[2:3] op_sel_hi:[1,0,1]
	v_pk_fma_f32 v[0:1], v[236:237], v[64:65], v[0:1] op_sel_hi:[1,0,1]
	ds_read2st64_b32 v[56:57], v49 offset1:8
	ds_read2st64_b32 v[58:59], v49 offset0:16 offset1:24
	ds_read2st64_b32 v[60:61], v49 offset0:32 offset1:40
	ds_read2st64_b32 v[62:63], v49 offset0:48 offset1:56
	ds_read_b32 v64, v49 offset:16384
	v_add_u32_e32 v49, 64, v49
	s_waitcnt lgkmcnt(5)
	v_mov_b32_e32 v76, v245
	v_mov_b32_e32 v78, v247
	v_mov_b32_e32 v80, v249
	v_mov_b32_e32 v82, v251
	s_waitcnt vmcnt(2)
	v_pk_fma_f32 v[34:35], v[242:243], v[244:245], v[34:35] op_sel_hi:[1,0,1]
	v_pk_fma_f32 v[32:33], v[240:241], v[244:245], v[32:33] op_sel_hi:[1,0,1]
	v_pk_fma_f32 v[30:31], v[242:243], v[76:77], v[30:31] op_sel_hi:[1,0,1]
	v_pk_fma_f32 v[28:29], v[240:241], v[76:77], v[28:29] op_sel_hi:[1,0,1]
	v_pk_fma_f32 v[26:27], v[242:243], v[246:247], v[26:27] op_sel_hi:[1,0,1]
	v_pk_fma_f32 v[24:25], v[240:241], v[246:247], v[24:25] op_sel_hi:[1,0,1]
	v_pk_fma_f32 v[22:23], v[242:243], v[78:79], v[22:23] op_sel_hi:[1,0,1]
	v_pk_fma_f32 v[20:21], v[240:241], v[78:79], v[20:21] op_sel_hi:[1,0,1]
	v_pk_fma_f32 v[18:19], v[242:243], v[248:249], v[18:19] op_sel_hi:[1,0,1]
	v_pk_fma_f32 v[16:17], v[240:241], v[248:249], v[16:17] op_sel_hi:[1,0,1]
	v_pk_fma_f32 v[14:15], v[242:243], v[80:81], v[14:15] op_sel_hi:[1,0,1]
	v_pk_fma_f32 v[12:13], v[240:241], v[80:81], v[12:13] op_sel_hi:[1,0,1]
	v_pk_fma_f32 v[10:11], v[242:243], v[250:251], v[10:11] op_sel_hi:[1,0,1]
	v_pk_fma_f32 v[8:9], v[240:241], v[250:251], v[8:9] op_sel_hi:[1,0,1]
	v_pk_fma_f32 v[6:7], v[242:243], v[82:83], v[6:7] op_sel_hi:[1,0,1]
	v_pk_fma_f32 v[4:5], v[240:241], v[82:83], v[4:5] op_sel_hi:[1,0,1]
	v_pk_fma_f32 v[2:3], v[242:243], v[74:75], v[2:3] op_sel_hi:[1,0,1]
	v_pk_fma_f32 v[0:1], v[240:241], v[74:75], v[0:1] op_sel_hi:[1,0,1]
	ds_read2st64_b32 v[244:245], v49 offset1:8
	ds_read2st64_b32 v[246:247], v49 offset0:16 offset1:24
	ds_read2st64_b32 v[248:249], v49 offset0:32 offset1:40
	ds_read2st64_b32 v[250:251], v49 offset0:48 offset1:56
	ds_read_b32 v74, v49 offset:16384
	v_add_u32_e32 v49, 64, v49
	s_waitcnt lgkmcnt(5)
	v_mov_b32_e32 v66, v57
	v_mov_b32_e32 v68, v59
	v_mov_b32_e32 v70, v61
	v_mov_b32_e32 v72, v63
	s_waitcnt vmcnt(1)
	v_pk_fma_f32 v[34:35], v[188:189], v[56:57], v[34:35] op_sel_hi:[1,0,1]
	v_pk_fma_f32 v[32:33], v[186:187], v[56:57], v[32:33] op_sel_hi:[1,0,1]
	v_pk_fma_f32 v[30:31], v[188:189], v[66:67], v[30:31] op_sel_hi:[1,0,1]
	v_pk_fma_f32 v[28:29], v[186:187], v[66:67], v[28:29] op_sel_hi:[1,0,1]
	v_pk_fma_f32 v[26:27], v[188:189], v[58:59], v[26:27] op_sel_hi:[1,0,1]
	v_pk_fma_f32 v[24:25], v[186:187], v[58:59], v[24:25] op_sel_hi:[1,0,1]
	v_pk_fma_f32 v[22:23], v[188:189], v[68:69], v[22:23] op_sel_hi:[1,0,1]
	v_pk_fma_f32 v[20:21], v[186:187], v[68:69], v[20:21] op_sel_hi:[1,0,1]
	v_pk_fma_f32 v[18:19], v[188:189], v[60:61], v[18:19] op_sel_hi:[1,0,1]
	v_pk_fma_f32 v[16:17], v[186:187], v[60:61], v[16:17] op_sel_hi:[1,0,1]
	v_pk_fma_f32 v[14:15], v[188:189], v[70:71], v[14:15] op_sel_hi:[1,0,1]
	v_pk_fma_f32 v[12:13], v[186:187], v[70:71], v[12:13] op_sel_hi:[1,0,1]
	v_pk_fma_f32 v[10:11], v[188:189], v[62:63], v[10:11] op_sel_hi:[1,0,1]
	v_pk_fma_f32 v[8:9], v[186:187], v[62:63], v[8:9] op_sel_hi:[1,0,1]
	v_pk_fma_f32 v[6:7], v[188:189], v[72:73], v[6:7] op_sel_hi:[1,0,1]
	v_pk_fma_f32 v[4:5], v[186:187], v[72:73], v[4:5] op_sel_hi:[1,0,1]
	v_pk_fma_f32 v[2:3], v[188:189], v[64:65], v[2:3] op_sel_hi:[1,0,1]
	v_pk_fma_f32 v[0:1], v[186:187], v[64:65], v[0:1] op_sel_hi:[1,0,1]
	s_waitcnt lgkmcnt(0)
	v_mov_b32_e32 v76, v245
	v_mov_b32_e32 v78, v247
	v_mov_b32_e32 v80, v249
	v_mov_b32_e32 v82, v251
	s_waitcnt vmcnt(0)
	v_pk_fma_f32 v[34:35], v[200:201], v[244:245], v[34:35] op_sel_hi:[1,0,1]
	v_pk_fma_f32 v[32:33], v[198:199], v[244:245], v[32:33] op_sel_hi:[1,0,1]
	v_pk_fma_f32 v[30:31], v[200:201], v[76:77], v[30:31] op_sel_hi:[1,0,1]
	v_pk_fma_f32 v[28:29], v[198:199], v[76:77], v[28:29] op_sel_hi:[1,0,1]
	v_pk_fma_f32 v[26:27], v[200:201], v[246:247], v[26:27] op_sel_hi:[1,0,1]
	v_pk_fma_f32 v[24:25], v[198:199], v[246:247], v[24:25] op_sel_hi:[1,0,1]
	v_pk_fma_f32 v[22:23], v[200:201], v[78:79], v[22:23] op_sel_hi:[1,0,1]
	v_pk_fma_f32 v[20:21], v[198:199], v[78:79], v[20:21] op_sel_hi:[1,0,1]
	v_pk_fma_f32 v[18:19], v[200:201], v[248:249], v[18:19] op_sel_hi:[1,0,1]
	v_pk_fma_f32 v[16:17], v[198:199], v[248:249], v[16:17] op_sel_hi:[1,0,1]
	v_pk_fma_f32 v[14:15], v[200:201], v[80:81], v[14:15] op_sel_hi:[1,0,1]
	v_pk_fma_f32 v[12:13], v[198:199], v[80:81], v[12:13] op_sel_hi:[1,0,1]
	v_pk_fma_f32 v[10:11], v[200:201], v[250:251], v[10:11] op_sel_hi:[1,0,1]
	v_pk_fma_f32 v[8:9], v[198:199], v[250:251], v[8:9] op_sel_hi:[1,0,1]
	v_pk_fma_f32 v[6:7], v[200:201], v[82:83], v[6:7] op_sel_hi:[1,0,1]
	v_pk_fma_f32 v[4:5], v[198:199], v[82:83], v[4:5] op_sel_hi:[1,0,1]
	v_pk_fma_f32 v[2:3], v[200:201], v[74:75], v[2:3] op_sel_hi:[1,0,1]
	v_pk_fma_f32 v[0:1], v[198:199], v[74:75], v[0:1] op_sel_hi:[1,0,1]
	s_or_b64 exec, exec, s[4:5]
